# v5 + K-loop compute segments start straight on the MFMAs: hipcc's redundant s_waitcnt lgkmcnt(0) after s_setprio 1 and the mid-burst s_setprio 0/1 toggle removed
# speedup vs baseline: 1.0264x; 1.0062x over previous
; #define PG8_STAGE(bufoff, gbase, voff) do { _Pragma("unroll") for (int _i = 0; _i < 2; ++_i) \
;         __builtin_amdgcn_global_load_lds((const unsigned*)((const char*)(gbase) + (voff)[_i]), (LAS unsigned*)(lds + (bufoff) + ldsw + _i * 8192), 16, 0, 0); } while (0)
; #define PG8_LDA(dst, b, h) do { _Pragma("unroll") for (int m = 0; m < 4; ++m) _Pragma("unroll") for (int k = 0; k < 2; ++k) dst[m][k] = *(const LAS bf16x8*)(lds + PG8_SA(b, h) + aoff + m * 2048 + k * KOFF); } while (0)
; #define PG8_LDB(dst, b, h) do { _Pragma("unroll") for (int n = 0; n < 2; ++n) _Pragma("unroll") for (int k = 0; k < 2; ++k) dst[n][k] = *(const LAS bf16x8*)(lds + PG8_SB(b, h) + boff + n * 2048 + k * KOFF); } while (0)
; #define PG8_WAIT_V(n) asm volatile("s_waitcnt vmcnt(" #n ")" ::: "memory")
; #define PG8_WAIT_L(n) asm volatile("s_waitcnt lgkmcnt(" #n ")" ::: "memory")
; #define PG8_BAR __builtin_amdgcn_s_barrier()
; #define PG8_SCHED __builtin_amdgcn_sched_barrier(0)
; template <class Epi, bool ALIGN_EPI = true, bool FP8 = false>
; __device__ __forceinline__ void gemm_phase(LAS unsigned char* lds, const Gemm g, const StaticOrder& S, const Epi& E, const int wid) {
;     ...
;             PG8_LDB(B0, 0, 0); PG8_LDB(B1, 0, 1); PG8_SCHED; PG8_LDA(At, 0, 0); PG8_STAGE(PG8_SA(1, 1), a1 + hstep, voffA);
;             PG8_WAIT_V(8); PG8_WAIT_L(0); PG8_BAR; PG8_MMA(0, 0, At, B0); PG8_MMA(0, 1, At, B1); PG8_BAR; PG8_SCHED;
;             PG8_LDA(At, 0, 1); PG8_STAGE(PG8_SB(0, 0), b2, voffB); PG8_STAGE(PG8_SB(0, 1), b2 + hstep, voffB); PG8_STAGE(PG8_SA(0, 0), a2, voffA);
;             PG8_WAIT_V(8); PG8_WAIT_L(0); PG8_BAR; PG8_MMA(1, 0, At, B0); PG8_MMA(1, 1, At, B1); PG8_BAR; PG8_SCHED;
.LBB0_506:
	ds_read_b128 v[146:149], v137
	ds_read_b128 v[154:157], v137 offset:1024
	ds_read_b128 v[158:161], v137 offset:2048
	ds_read_b128 v[162:165], v137 offset:3072
	ds_read_b128 v[166:169], v152
	ds_read_b128 v[170:173], v152 offset:1024
	ds_read_b128 v[174:177], v152 offset:2048
	ds_read_b128 v[178:181], v152 offset:3072
	s_add_i32 s52, s34, 2
	s_add_u32 s35, s30, 0xfff80080
	s_addc_u32 s36, s31, -1
	s_cmp_eq_u32 s39, s34
	s_cselect_b32 s34, s38, s42
	s_cselect_b32 s37, s3, s36
	s_cselect_b32 s36, s23, s35
	s_cselect_b32 s35, s25, s43
	v_lshl_add_u64 v[214:215], s[30:31], 0, v[140:141]
	s_add_i32 m0, s75, 0xc000
	ds_read_b128 v[182:185], v153
	ds_read_b128 v[186:189], v153 offset:1024
	ds_read_b128 v[190:193], v153 offset:2048
	ds_read_b128 v[194:197], v153 offset:3072
	ds_read_b128 v[198:201], v153 offset:4096
	ds_read_b128 v[202:205], v153 offset:5120
	ds_read_b128 v[206:209], v153 offset:6144
	ds_read_b128 v[210:213], v153 offset:7168
	global_load_lds_dwordx4 v[214:215], off
	v_lshl_add_u64 v[214:215], s[30:31], 0, v[142:143]
	s_add_i32 m0, s75, 0xe000
	s_nop 0
	global_load_lds_dwordx4 v[214:215], off
	s_waitcnt vmcnt(8)
	s_waitcnt lgkmcnt(0)
	s_barrier
	s_setprio 1
	v_mfma_f32_16x16x32_bf16 v[124:127], v[146:149], v[182:185], v[124:127]
	v_mfma_f32_16x16x32_bf16 v[120:123], v[158:161], v[182:185], v[120:123]
	v_mfma_f32_16x16x32_bf16 v[108:111], v[146:149], v[190:193], v[108:111]
	v_mfma_f32_16x16x32_bf16 v[104:107], v[158:161], v[190:193], v[104:107]
	v_mfma_f32_16x16x32_bf16 v[92:95], v[146:149], v[198:201], v[92:95]
	v_mfma_f32_16x16x32_bf16 v[88:91], v[158:161], v[198:201], v[88:91]
	v_mfma_f32_16x16x32_bf16 v[76:79], v[146:149], v[206:209], v[76:79]
	v_mfma_f32_16x16x32_bf16 v[72:75], v[158:161], v[206:209], v[72:75]
	v_mfma_f32_16x16x32_bf16 v[124:127], v[154:157], v[186:189], v[124:127]
	v_mfma_f32_16x16x32_bf16 v[120:123], v[162:165], v[186:189], v[120:123]
	v_mfma_f32_16x16x32_bf16 v[108:111], v[154:157], v[194:197], v[108:111]
	v_mfma_f32_16x16x32_bf16 v[104:107], v[162:165], v[194:197], v[104:107]
	v_mfma_f32_16x16x32_bf16 v[92:95], v[154:157], v[202:205], v[92:95]
	v_mfma_f32_16x16x32_bf16 v[88:91], v[162:165], v[202:205], v[88:91]
	v_mfma_f32_16x16x32_bf16 v[76:79], v[154:157], v[210:213], v[76:79]
	v_mfma_f32_16x16x32_bf16 v[72:75], v[162:165], v[210:213], v[72:75]
	v_mfma_f32_16x16x32_bf16 v[116:119], v[166:169], v[182:185], v[116:119]
	v_mfma_f32_16x16x32_bf16 v[112:115], v[174:177], v[182:185], v[112:115]
	v_mfma_f32_16x16x32_bf16 v[100:103], v[166:169], v[190:193], v[100:103]
	v_mfma_f32_16x16x32_bf16 v[96:99], v[174:177], v[190:193], v[96:99]
	v_mfma_f32_16x16x32_bf16 v[84:87], v[166:169], v[198:201], v[84:87]
	v_mfma_f32_16x16x32_bf16 v[80:83], v[174:177], v[198:201], v[80:83]
	v_mfma_f32_16x16x32_bf16 v[68:71], v[166:169], v[206:209], v[68:71]
	v_mfma_f32_16x16x32_bf16 v[64:67], v[174:177], v[206:209], v[64:67]
	v_mfma_f32_16x16x32_bf16 v[116:119], v[170:173], v[186:189], v[116:119]
	v_mfma_f32_16x16x32_bf16 v[112:115], v[178:181], v[186:189], v[112:115]
	v_mfma_f32_16x16x32_bf16 v[100:103], v[170:173], v[194:197], v[100:103]
	v_mfma_f32_16x16x32_bf16 v[96:99], v[178:181], v[194:197], v[96:99]
	v_mfma_f32_16x16x32_bf16 v[84:87], v[170:173], v[202:205], v[84:87]
	v_mfma_f32_16x16x32_bf16 v[80:83], v[178:181], v[202:205], v[80:83]
	v_mfma_f32_16x16x32_bf16 v[68:71], v[170:173], v[210:213], v[68:71]
	v_mfma_f32_16x16x32_bf16 v[64:67], v[178:181], v[210:213], v[64:67]
	s_setprio 0
	s_barrier
	s_add_i32 s54, s86, s48
	v_lshl_add_u64 v[214:215], s[34:35], 0, v[132:133]
	s_mov_b32 m0, s54
	ds_read_b128 v[182:185], v153 offset:16384
	ds_read_b128 v[186:189], v153 offset:17408
	ds_read_b128 v[190:193], v153 offset:18432
	ds_read_b128 v[194:197], v153 offset:19456
	ds_read_b128 v[198:201], v153 offset:20480
	ds_read_b128 v[202:205], v153 offset:21504
	ds_read_b128 v[206:209], v153 offset:22528
	ds_read_b128 v[210:213], v153 offset:23552
	global_load_lds_dwordx4 v[214:215], off
	s_add_i32 m0, s54, 0x2000
	s_add_u32 s64, s34, 0x80000
	v_lshl_add_u64 v[216:217], s[34:35], 0, v[128:129]
	s_addc_u32 s65, s35, 0
	s_add_i32 s54, s87, s48
	global_load_lds_dwordx4 v[216:217], off
	v_lshl_add_u64 v[218:219], s[64:65], 0, v[132:133]
	s_mov_b32 m0, s54
	v_lshl_add_u64 v[220:221], s[36:37], 0, v[130:131]
	global_load_lds_dwordx4 v[218:219], off
	v_lshl_add_u64 v[218:219], s[64:65], 0, v[128:129]
	s_add_i32 m0, s54, 0x2000
	s_nop 0
	global_load_lds_dwordx4 v[218:219], off
	v_lshl_add_u64 v[218:219], s[36:37], 0, v[134:135]
	s_mov_b32 m0, s75
	s_nop 0
	global_load_lds_dwordx4 v[218:219], off
	s_mov_b32 m0, s76
	s_nop 0
	global_load_lds_dwordx4 v[220:221], off
	s_waitcnt vmcnt(8)
	s_waitcnt lgkmcnt(0)
	s_barrier
; #define PG8_STAGE(bufoff, gbase, voff) do { _Pragma("unroll") for (int _i = 0; _i < 2; ++_i) \
;         __builtin_amdgcn_global_load_lds((const unsigned*)((const char*)(gbase) + (voff)[_i]), (LAS unsigned*)(lds + (bufoff) + ldsw + _i * 8192), 16, 0, 0); } while (0)
; #define PG8_LDA(dst, b, h) do { _Pragma("unroll") for (int m = 0; m < 4; ++m) _Pragma("unroll") for (int k = 0; k < 2; ++k) dst[m][k] = *(const LAS bf16x8*)(lds + PG8_SA(b, h) + aoff + m * 2048 + k * KOFF); } while (0)
; #define PG8_LDB(dst, b, h) do { _Pragma("unroll") for (int n = 0; n < 2; ++n) _Pragma("unroll") for (int k = 0; k < 2; ++k) dst[n][k] = *(const LAS bf16x8*)(lds + PG8_SB(b, h) + boff + n * 2048 + k * KOFF); } while (0)
; #define PG8_WAIT_V(n) asm volatile("s_waitcnt vmcnt(" #n ")" ::: "memory")
; #define PG8_WAIT_L(n) asm volatile("s_waitcnt lgkmcnt(" #n ")" ::: "memory")
; #define PG8_BAR __builtin_amdgcn_s_barrier()
; #define PG8_SCHED __builtin_amdgcn_sched_barrier(0)
; template <class Epi, bool ALIGN_EPI = true, bool FP8 = false>
; __device__ __forceinline__ void gemm_phase(LAS unsigned char* lds, const Gemm g, const StaticOrder& S, const Epi& E, const int wid) {
;     ...
;             PG8_WAIT_V(8); PG8_WAIT_L(0); PG8_BAR; PG8_MMA(1, 0, At, B0); PG8_MMA(1, 1, At, B1); PG8_BAR; PG8_SCHED;
;             PG8_LDB(B0, 1, 0); PG8_LDB(B1, 1, 1); PG8_SCHED; PG8_LDA(At, 1, 0); PG8_STAGE(PG8_SA(0, 1), a2 + hstep, voffA);
;             PG8_WAIT_V(8); PG8_WAIT_L(0); PG8_BAR; PG8_MMA(0, 0, At, B0); PG8_MMA(0, 1, At, B1); PG8_BAR; PG8_SCHED;
	s_setprio 1
	v_mfma_f32_16x16x32_bf16 v[60:63], v[146:149], v[182:185], v[60:63]
	v_mfma_f32_16x16x32_bf16 v[56:59], v[158:161], v[182:185], v[56:59]
	v_mfma_f32_16x16x32_bf16 v[44:47], v[146:149], v[190:193], v[44:47]
	v_mfma_f32_16x16x32_bf16 v[40:43], v[158:161], v[190:193], v[40:43]
	v_mfma_f32_16x16x32_bf16 v[28:31], v[146:149], v[198:201], v[28:31]
	v_mfma_f32_16x16x32_bf16 v[24:27], v[158:161], v[198:201], v[24:27]
	v_mfma_f32_16x16x32_bf16 v[12:15], v[146:149], v[206:209], v[12:15]
	v_mfma_f32_16x16x32_bf16 v[8:11], v[158:161], v[206:209], v[8:11]
	v_mfma_f32_16x16x32_bf16 v[60:63], v[154:157], v[186:189], v[60:63]
	v_mfma_f32_16x16x32_bf16 v[56:59], v[162:165], v[186:189], v[56:59]
	v_mfma_f32_16x16x32_bf16 v[44:47], v[154:157], v[194:197], v[44:47]
	v_mfma_f32_16x16x32_bf16 v[40:43], v[162:165], v[194:197], v[40:43]
	v_mfma_f32_16x16x32_bf16 v[28:31], v[154:157], v[202:205], v[28:31]
	v_mfma_f32_16x16x32_bf16 v[24:27], v[162:165], v[202:205], v[24:27]
	v_mfma_f32_16x16x32_bf16 v[12:15], v[154:157], v[210:213], v[12:15]
	v_mfma_f32_16x16x32_bf16 v[8:11], v[162:165], v[210:213], v[8:11]
	v_mfma_f32_16x16x32_bf16 v[52:55], v[166:169], v[182:185], v[52:55]
	v_mfma_f32_16x16x32_bf16 v[48:51], v[174:177], v[182:185], v[48:51]
	v_mfma_f32_16x16x32_bf16 v[36:39], v[166:169], v[190:193], v[36:39]
	v_mfma_f32_16x16x32_bf16 v[32:35], v[174:177], v[190:193], v[32:35]
	v_mfma_f32_16x16x32_bf16 v[20:23], v[166:169], v[198:201], v[20:23]
	v_mfma_f32_16x16x32_bf16 v[16:19], v[174:177], v[198:201], v[16:19]
	v_mfma_f32_16x16x32_bf16 v[4:7], v[166:169], v[206:209], v[4:7]
	v_mfma_f32_16x16x32_bf16 v[0:3], v[174:177], v[206:209], v[0:3]
	v_mfma_f32_16x16x32_bf16 v[52:55], v[170:173], v[186:189], v[52:55]
	v_mfma_f32_16x16x32_bf16 v[48:51], v[178:181], v[186:189], v[48:51]
	v_mfma_f32_16x16x32_bf16 v[36:39], v[170:173], v[194:197], v[36:39]
	v_mfma_f32_16x16x32_bf16 v[32:35], v[178:181], v[194:197], v[32:35]
	v_mfma_f32_16x16x32_bf16 v[20:23], v[170:173], v[202:205], v[20:23]
	v_mfma_f32_16x16x32_bf16 v[16:19], v[178:181], v[202:205], v[16:19]
	v_mfma_f32_16x16x32_bf16 v[4:7], v[170:173], v[210:213], v[4:7]
	v_mfma_f32_16x16x32_bf16 v[0:3], v[178:181], v[210:213], v[0:3]
	s_setprio 0
	s_barrier
	s_add_i32 s54, 0, 0x18000
	s_add_i32 s64, 0, 0x1c000
	v_add_u32_e32 v162, s54, v150
	v_add_u32_e32 v178, s64, v150
	ds_read_b128 v[146:149], v162
	ds_read_b128 v[154:157], v162 offset:1024
	ds_read_b128 v[158:161], v162 offset:2048
	ds_read_b128 v[162:165], v162 offset:3072
	ds_read_b128 v[166:169], v178
	ds_read_b128 v[170:173], v178 offset:1024
	ds_read_b128 v[174:177], v178 offset:2048
	ds_read_b128 v[178:181], v178 offset:3072
	s_add_u32 s36, s36, 0x80000
	s_addc_u32 s37, s37, 0
	s_mov_b32 m0, s77
	v_lshl_add_u64 v[222:223], s[36:37], 0, v[134:135]
	ds_read_b128 v[182:185], v153 offset:32768
	ds_read_b128 v[186:189], v153 offset:33792
	ds_read_b128 v[190:193], v153 offset:34816
	ds_read_b128 v[194:197], v153 offset:35840
	ds_read_b128 v[198:201], v153 offset:36864
	ds_read_b128 v[202:205], v153 offset:37888
	ds_read_b128 v[206:209], v153 offset:38912
	ds_read_b128 v[210:213], v153 offset:39936
	global_load_lds_dwordx4 v[222:223], off
	v_lshl_add_u64 v[222:223], s[36:37], 0, v[130:131]
	s_mov_b32 m0, s78
	s_nop 0
	global_load_lds_dwordx4 v[222:223], off
	s_waitcnt vmcnt(8)
	s_waitcnt lgkmcnt(0)
	s_barrier
	s_setprio 1
	v_mfma_f32_16x16x32_bf16 v[124:127], v[146:149], v[182:185], v[124:127]
	v_mfma_f32_16x16x32_bf16 v[120:123], v[158:161], v[182:185], v[120:123]
	v_mfma_f32_16x16x32_bf16 v[108:111], v[146:149], v[190:193], v[108:111]
	v_mfma_f32_16x16x32_bf16 v[104:107], v[158:161], v[190:193], v[104:107]
	v_mfma_f32_16x16x32_bf16 v[92:95], v[146:149], v[198:201], v[92:95]
	v_mfma_f32_16x16x32_bf16 v[88:91], v[158:161], v[198:201], v[88:91]
	v_mfma_f32_16x16x32_bf16 v[76:79], v[146:149], v[206:209], v[76:79]
	v_mfma_f32_16x16x32_bf16 v[72:75], v[158:161], v[206:209], v[72:75]
	v_mfma_f32_16x16x32_bf16 v[124:127], v[154:157], v[186:189], v[124:127]
	v_mfma_f32_16x16x32_bf16 v[120:123], v[162:165], v[186:189], v[120:123]
	v_mfma_f32_16x16x32_bf16 v[108:111], v[154:157], v[194:197], v[108:111]
	v_mfma_f32_16x16x32_bf16 v[104:107], v[162:165], v[194:197], v[104:107]
	v_mfma_f32_16x16x32_bf16 v[92:95], v[154:157], v[202:205], v[92:95]
	v_mfma_f32_16x16x32_bf16 v[88:91], v[162:165], v[202:205], v[88:91]
	v_mfma_f32_16x16x32_bf16 v[76:79], v[154:157], v[210:213], v[76:79]
	v_mfma_f32_16x16x32_bf16 v[72:75], v[162:165], v[210:213], v[72:75]
	v_mfma_f32_16x16x32_bf16 v[116:119], v[166:169], v[182:185], v[116:119]
	v_mfma_f32_16x16x32_bf16 v[112:115], v[174:177], v[182:185], v[112:115]
	v_mfma_f32_16x16x32_bf16 v[100:103], v[166:169], v[190:193], v[100:103]
	v_mfma_f32_16x16x32_bf16 v[96:99], v[174:177], v[190:193], v[96:99]
	v_mfma_f32_16x16x32_bf16 v[84:87], v[166:169], v[198:201], v[84:87]
	v_mfma_f32_16x16x32_bf16 v[80:83], v[174:177], v[198:201], v[80:83]
	v_mfma_f32_16x16x32_bf16 v[68:71], v[166:169], v[206:209], v[68:71]
	v_mfma_f32_16x16x32_bf16 v[64:67], v[174:177], v[206:209], v[64:67]
	v_mfma_f32_16x16x32_bf16 v[116:119], v[170:173], v[186:189], v[116:119]
	v_mfma_f32_16x16x32_bf16 v[112:115], v[178:181], v[186:189], v[112:115]
	v_mfma_f32_16x16x32_bf16 v[100:103], v[170:173], v[194:197], v[100:103]
	v_mfma_f32_16x16x32_bf16 v[96:99], v[178:181], v[194:197], v[96:99]
	v_mfma_f32_16x16x32_bf16 v[84:87], v[170:173], v[202:205], v[84:87]
	v_mfma_f32_16x16x32_bf16 v[80:83], v[178:181], v[202:205], v[80:83]
	v_mfma_f32_16x16x32_bf16 v[68:71], v[170:173], v[210:213], v[68:71]
	v_mfma_f32_16x16x32_bf16 v[64:67], v[178:181], v[210:213], v[64:67]
	s_setprio 0
	s_barrier
; #define PG8_STAGE(bufoff, gbase, voff) do { _Pragma("unroll") for (int _i = 0; _i < 2; ++_i) \
;         __builtin_amdgcn_global_load_lds((const unsigned*)((const char*)(gbase) + (voff)[_i]), (LAS unsigned*)(lds + (bufoff) + ldsw + _i * 8192), 16, 0, 0); } while (0)
; #define PG8_LDA(dst, b, h) do { _Pragma("unroll") for (int m = 0; m < 4; ++m) _Pragma("unroll") for (int k = 0; k < 2; ++k) dst[m][k] = *(const LAS bf16x8*)(lds + PG8_SA(b, h) + aoff + m * 2048 + k * KOFF); } while (0)
; #define PG8_WAIT_V(n) asm volatile("s_waitcnt vmcnt(" #n ")" ::: "memory")
; #define PG8_WAIT_L(n) asm volatile("s_waitcnt lgkmcnt(" #n ")" ::: "memory")
; #define PG8_BAR __builtin_amdgcn_s_barrier()
; #define PG8_SCHED __builtin_amdgcn_sched_barrier(0)
; template <class Epi, bool ALIGN_EPI = true, bool FP8 = false>
; __device__ __forceinline__ void gemm_phase(LAS unsigned char* lds, const Gemm g, const StaticOrder& S, const Epi& E, const int wid) {
;     ...
;             PG8_LDA(At, 1, 1); PG8_STAGE(PG8_SB(1, 0), b3, voffB); PG8_STAGE(PG8_SB(1, 1), b3 + hstep, voffB); PG8_STAGE(PG8_SA(1, 0), a3, voffA);
;             PG8_WAIT_V(8); PG8_WAIT_L(0); PG8_BAR; PG8_MMA(1, 0, At, B0); PG8_MMA(1, 1, At, B1); PG8_BAR; PG8_SCHED;
;         }
	s_add_i32 s36, s54, s48
	v_lshl_add_u64 v[214:215], v[214:215], 0, s[16:17]
	s_mov_b32 m0, s36
	ds_read_b128 v[182:185], v153 offset:49152
	ds_read_b128 v[186:189], v153 offset:50176
	ds_read_b128 v[190:193], v153 offset:51200
	ds_read_b128 v[194:197], v153 offset:52224
	ds_read_b128 v[198:201], v153 offset:53248
	ds_read_b128 v[202:205], v153 offset:54272
	ds_read_b128 v[206:209], v153 offset:55296
	ds_read_b128 v[210:213], v153 offset:56320
	global_load_lds_dwordx4 v[214:215], off
	s_add_i32 m0, s36, 0x2000
	s_add_u32 s34, s34, 0x80080
	v_lshl_add_u64 v[214:215], v[216:217], 0, s[16:17]
	s_addc_u32 s35, s35, 0
	s_add_i32 s36, s64, s48
	global_load_lds_dwordx4 v[214:215], off
	v_lshl_add_u64 v[214:215], s[34:35], 0, v[132:133]
	s_mov_b32 m0, s36
	s_nop 0
	global_load_lds_dwordx4 v[214:215], off
	v_lshl_add_u64 v[214:215], s[34:35], 0, v[128:129]
	s_add_i32 m0, s36, 0x2000
	s_nop 0
	global_load_lds_dwordx4 v[214:215], off
	v_lshl_add_u64 v[214:215], v[218:219], 0, s[16:17]
	s_mov_b32 m0, s83
	s_nop 0
	global_load_lds_dwordx4 v[214:215], off
	v_lshl_add_u64 v[214:215], v[220:221], 0, s[16:17]
	s_mov_b32 m0, s84
	s_nop 0
	global_load_lds_dwordx4 v[214:215], off
	s_waitcnt vmcnt(8)
	s_waitcnt lgkmcnt(0)
	s_barrier
	s_setprio 1
	v_mfma_f32_16x16x32_bf16 v[60:63], v[146:149], v[182:185], v[60:63]
	v_mfma_f32_16x16x32_bf16 v[56:59], v[158:161], v[182:185], v[56:59]
	v_mfma_f32_16x16x32_bf16 v[44:47], v[146:149], v[190:193], v[44:47]
	v_mfma_f32_16x16x32_bf16 v[40:43], v[158:161], v[190:193], v[40:43]
	v_mfma_f32_16x16x32_bf16 v[28:31], v[146:149], v[198:201], v[28:31]
	v_mfma_f32_16x16x32_bf16 v[24:27], v[158:161], v[198:201], v[24:27]
	v_mfma_f32_16x16x32_bf16 v[12:15], v[146:149], v[206:209], v[12:15]
	v_mfma_f32_16x16x32_bf16 v[8:11], v[158:161], v[206:209], v[8:11]
	v_mfma_f32_16x16x32_bf16 v[60:63], v[154:157], v[186:189], v[60:63]
	v_mfma_f32_16x16x32_bf16 v[56:59], v[162:165], v[186:189], v[56:59]
	v_mfma_f32_16x16x32_bf16 v[44:47], v[154:157], v[194:197], v[44:47]
	v_mfma_f32_16x16x32_bf16 v[40:43], v[162:165], v[194:197], v[40:43]
	v_mfma_f32_16x16x32_bf16 v[28:31], v[154:157], v[202:205], v[28:31]
	v_mfma_f32_16x16x32_bf16 v[24:27], v[162:165], v[202:205], v[24:27]
	v_mfma_f32_16x16x32_bf16 v[12:15], v[154:157], v[210:213], v[12:15]
	v_mfma_f32_16x16x32_bf16 v[8:11], v[162:165], v[210:213], v[8:11]
	v_mfma_f32_16x16x32_bf16 v[52:55], v[166:169], v[182:185], v[52:55]
	v_mfma_f32_16x16x32_bf16 v[48:51], v[174:177], v[182:185], v[48:51]
	v_mfma_f32_16x16x32_bf16 v[36:39], v[166:169], v[190:193], v[36:39]
	v_mfma_f32_16x16x32_bf16 v[32:35], v[174:177], v[190:193], v[32:35]
	v_mfma_f32_16x16x32_bf16 v[20:23], v[166:169], v[198:201], v[20:23]
	v_mfma_f32_16x16x32_bf16 v[16:19], v[174:177], v[198:201], v[16:19]
	v_mfma_f32_16x16x32_bf16 v[4:7], v[166:169], v[206:209], v[4:7]
	v_mfma_f32_16x16x32_bf16 v[0:3], v[174:177], v[206:209], v[0:3]
	v_mfma_f32_16x16x32_bf16 v[52:55], v[170:173], v[186:189], v[52:55]
	v_mfma_f32_16x16x32_bf16 v[48:51], v[178:181], v[186:189], v[48:51]
	v_mfma_f32_16x16x32_bf16 v[36:39], v[170:173], v[194:197], v[36:39]
	v_mfma_f32_16x16x32_bf16 v[32:35], v[178:181], v[194:197], v[32:35]
	v_mfma_f32_16x16x32_bf16 v[20:23], v[170:173], v[202:205], v[20:23]
	v_mfma_f32_16x16x32_bf16 v[16:19], v[178:181], v[202:205], v[16:19]
	v_mfma_f32_16x16x32_bf16 v[4:7], v[170:173], v[210:213], v[4:7]
	v_mfma_f32_16x16x32_bf16 v[0:3], v[178:181], v[210:213], v[0:3]
	s_setprio 0
	s_barrier
	s_add_u32 s30, s30, 0x100
	s_addc_u32 s31, s31, 0
	s_add_u32 s42, s42, 0x100
	s_addc_u32 s43, s43, 0
	s_cmp_ge_u32 s52, s9
	s_mov_b32 s34, s52
	s_cbranch_scc0 .LBB0_506
	s_and_b64 vcc, exec, s[12:13]
	s_cbranch_vccz .LBB0_509

; #define PG8_STAGE(bufoff, gbase, voff) do { _Pragma("unroll") for (int _i = 0; _i < 2; ++_i) \
;         __builtin_amdgcn_global_load_lds((const unsigned*)((const char*)(gbase) + (voff)[_i]), (LAS unsigned*)(lds + (bufoff) + ldsw + _i * 8192), 16, 0, 0); } while (0)
; #define PG8_LDA(dst, b, h) do { _Pragma("unroll") for (int m = 0; m < 4; ++m) _Pragma("unroll") for (int k = 0; k < 2; ++k) dst[m][k] = *(const LAS bf16x8*)(lds + PG8_SA(b, h) + aoff + m * 2048 + k * KOFF); } while (0)
; #define PG8_LDB(dst, b, h) do { _Pragma("unroll") for (int n = 0; n < 2; ++n) _Pragma("unroll") for (int k = 0; k < 2; ++k) dst[n][k] = *(const LAS bf16x8*)(lds + PG8_SB(b, h) + boff + n * 2048 + k * KOFF); } while (0)
; #define PG8_WAIT_V(n) asm volatile("s_waitcnt vmcnt(" #n ")" ::: "memory")
; #define PG8_WAIT_L(n) asm volatile("s_waitcnt lgkmcnt(" #n ")" ::: "memory")
; #define PG8_BAR __builtin_amdgcn_s_barrier()
; #define PG8_SCHED __builtin_amdgcn_sched_barrier(0)
; template <class Epi, bool ALIGN_EPI = true, bool FP8 = false>
; __device__ __forceinline__ void gemm_phase(LAS unsigned char* lds, const Gemm g, const StaticOrder& S, const Epi& E, const int wid) {
;     ...
;             PG8_LDB(B0, 0, 0); PG8_LDB(B1, 0, 1); PG8_SCHED; PG8_LDA(At, 0, 0); PG8_STAGE(PG8_SA(1, 1), a1 + hstep, voffA);
;             PG8_WAIT_V(8); PG8_WAIT_L(0); PG8_BAR; PG8_MMA(0, 0, At, B0); PG8_MMA(0, 1, At, B1); PG8_BAR; PG8_SCHED;
;             PG8_LDA(At, 0, 1); PG8_STAGE(PG8_SB(0, 0), b2, voffB); PG8_STAGE(PG8_SB(0, 1), b2 + hstep, voffB); PG8_STAGE(PG8_SA(0, 0), a2, voffA);
;             PG8_WAIT_V(8); PG8_WAIT_L(0); PG8_BAR; PG8_MMA(1, 0, At, B0); PG8_MMA(1, 1, At, B1); PG8_BAR; PG8_SCHED;
.LBB0_572:
	ds_read_b128 v[152:155], v190
	ds_read_b128 v[156:159], v190 offset:1024
	ds_read_b128 v[144:147], v190 offset:2048
	ds_read_b128 v[148:151], v190 offset:3072
	ds_read_b128 v[136:139], v191
	ds_read_b128 v[140:143], v191 offset:1024
	ds_read_b128 v[128:131], v191 offset:2048
	ds_read_b128 v[132:135], v191 offset:3072
	s_add_i32 s3, s34, 2
	s_add_u32 s35, s30, 0xfffc0080
	s_addc_u32 s36, s31, -1
	s_cmp_eq_u32 s86, s34
	s_cselect_b32 s34, s85, s87
	s_cselect_b32 s37, s21, s36
	s_cselect_b32 s36, s23, s35
	s_cselect_b32 s35, s84, s88
	v_lshl_add_u64 v[220:221], s[30:31], 0, v[170:171]
	s_add_i32 m0, s27, 0xc000
	ds_read_b128 v[178:181], v192
	ds_read_b128 v[182:185], v192 offset:1024
	ds_read_b128 v[196:199], v192 offset:2048
	ds_read_b128 v[200:203], v192 offset:3072
	ds_read_b128 v[204:207], v192 offset:4096
	ds_read_b128 v[208:211], v192 offset:5120
	ds_read_b128 v[212:215], v192 offset:6144
	ds_read_b128 v[216:219], v192 offset:7168
	global_load_lds_dwordx4 v[220:221], off
	v_lshl_add_u64 v[220:221], s[30:31], 0, v[172:173]
	s_add_i32 m0, s27, 0xe000
	s_nop 0
	global_load_lds_dwordx4 v[220:221], off
	s_waitcnt vmcnt(8)
	s_waitcnt lgkmcnt(0)
	s_barrier
	s_setprio 1
	v_mfma_f32_16x16x128_f8f6f4 v[120:123], v[152:159], v[178:185], v[120:123]
	v_mfma_f32_16x16x128_f8f6f4 v[124:127], v[144:151], v[178:185], v[124:127]
	v_mfma_f32_16x16x128_f8f6f4 v[112:115], v[152:159], v[196:203], v[112:115]
	v_mfma_f32_16x16x128_f8f6f4 v[116:119], v[144:151], v[196:203], v[116:119]
	v_mfma_f32_16x16x128_f8f6f4 v[104:107], v[152:159], v[204:211], v[104:107]
	v_mfma_f32_16x16x128_f8f6f4 v[108:111], v[144:151], v[204:211], v[108:111]
	v_mfma_f32_16x16x128_f8f6f4 v[88:91], v[152:159], v[212:219], v[88:91]
	v_mfma_f32_16x16x128_f8f6f4 v[92:95], v[144:151], v[212:219], v[92:95]
	v_mfma_f32_16x16x128_f8f6f4 v[96:99], v[136:143], v[178:185], v[96:99]
	v_mfma_f32_16x16x128_f8f6f4 v[100:103], v[128:135], v[178:185], v[100:103]
	v_mfma_f32_16x16x128_f8f6f4 v[80:83], v[136:143], v[196:203], v[80:83]
	v_mfma_f32_16x16x128_f8f6f4 v[84:87], v[128:135], v[196:203], v[84:87]
	v_mfma_f32_16x16x128_f8f6f4 v[72:75], v[136:143], v[204:211], v[72:75]
	v_mfma_f32_16x16x128_f8f6f4 v[76:79], v[128:135], v[204:211], v[76:79]
	v_mfma_f32_16x16x128_f8f6f4 v[64:67], v[136:143], v[212:219], v[64:67]
	v_mfma_f32_16x16x128_f8f6f4 v[68:71], v[128:135], v[212:219], v[68:71]
	s_setprio 0
	s_barrier
	s_add_i32 s42, s75, s48
	v_lshl_add_u64 v[178:179], s[34:35], 0, v[164:165]
	s_mov_b32 m0, s42
	ds_read_b128 v[196:199], v192 offset:16384
	ds_read_b128 v[200:203], v192 offset:17408
	ds_read_b128 v[204:207], v192 offset:18432
	ds_read_b128 v[208:211], v192 offset:19456
	ds_read_b128 v[212:215], v192 offset:20480
	ds_read_b128 v[216:219], v192 offset:21504
	ds_read_b128 v[220:223], v192 offset:22528
	ds_read_b128 v[224:227], v192 offset:23552
	global_load_lds_dwordx4 v[178:179], off
	s_add_i32 m0, s42, 0x2000
	s_add_u32 s42, s34, 0x40000
	v_lshl_add_u64 v[180:181], s[34:35], 0, v[160:161]
	s_addc_u32 s43, s35, 0
	s_add_i32 s52, s76, s48
	global_load_lds_dwordx4 v[180:181], off
	v_lshl_add_u64 v[182:183], s[42:43], 0, v[164:165]
	s_mov_b32 m0, s52
	v_lshl_add_u64 v[184:185], s[36:37], 0, v[162:163]
	global_load_lds_dwordx4 v[182:183], off
	v_lshl_add_u64 v[182:183], s[42:43], 0, v[160:161]
	s_add_i32 m0, s52, 0x2000
	s_nop 0
	global_load_lds_dwordx4 v[182:183], off
	v_lshl_add_u64 v[182:183], s[36:37], 0, v[166:167]
	s_mov_b32 m0, s27
	s_nop 0
	global_load_lds_dwordx4 v[182:183], off
	s_mov_b32 m0, s55
	s_nop 0
	global_load_lds_dwordx4 v[184:185], off
	s_waitcnt vmcnt(8)
	s_waitcnt lgkmcnt(0)
	s_barrier
	s_setprio 1
	v_mfma_f32_16x16x128_f8f6f4 v[56:59], v[152:159], v[196:203], v[56:59]
	v_mfma_f32_16x16x128_f8f6f4 v[60:63], v[144:151], v[196:203], v[60:63]
	v_mfma_f32_16x16x128_f8f6f4 v[48:51], v[152:159], v[204:211], v[48:51]
	v_mfma_f32_16x16x128_f8f6f4 v[52:55], v[144:151], v[204:211], v[52:55]
	v_mfma_f32_16x16x128_f8f6f4 v[40:43], v[152:159], v[212:219], v[40:43]
	v_mfma_f32_16x16x128_f8f6f4 v[44:47], v[144:151], v[212:219], v[44:47]
	v_mfma_f32_16x16x128_f8f6f4 v[228:231], v[152:159], v[220:227], v[24:27]
	v_mfma_f32_16x16x128_f8f6f4 v[232:235], v[144:151], v[220:227], v[28:31]
	v_mfma_f32_16x16x128_f8f6f4 v[236:239], v[136:143], v[196:203], v[32:35]
	v_mfma_f32_16x16x128_f8f6f4 v[240:243], v[128:135], v[196:203], v[36:39]
	v_mfma_f32_16x16x128_f8f6f4 v[244:247], v[136:143], v[204:211], v[16:19]
	v_mfma_f32_16x16x128_f8f6f4 v[204:207], v[128:135], v[204:211], v[20:23]
	v_mfma_f32_16x16x128_f8f6f4 v[208:211], v[136:143], v[212:219], v[8:11]
	v_mfma_f32_16x16x128_f8f6f4 v[212:215], v[128:135], v[212:219], v[12:15]
	v_mfma_f32_16x16x128_f8f6f4 v[216:219], v[136:143], v[220:227], v[0:3]
	v_mfma_f32_16x16x128_f8f6f4 v[220:223], v[128:135], v[220:227], v[4:7]
	s_setprio 0
	s_barrier
	s_add_i32 s42, 0, 0x18000
	s_add_i32 s43, 0, 0x1c000
	s_nop 0
	v_add_u32_e32 v12, s42, v187
	v_add_u32_e32 v16, s43, v187
	ds_read_b128 v[0:3], v12
	ds_read_b128 v[4:7], v12 offset:1024
	ds_read_b128 v[8:11], v12 offset:2048
	ds_read_b128 v[12:15], v12 offset:3072
	ds_read_b128 v[128:131], v16
	ds_read_b128 v[132:135], v16 offset:1024
	ds_read_b128 v[136:139], v16 offset:2048
	ds_read_b128 v[140:143], v16 offset:3072
	s_add_u32 s36, s36, 0x40000
	s_addc_u32 s37, s37, 0
	s_mov_b32 m0, s64
	v_lshl_add_u64 v[152:153], s[36:37], 0, v[166:167]
	ds_read_b128 v[16:19], v192 offset:32768
	ds_read_b128 v[20:23], v192 offset:33792
	ds_read_b128 v[24:27], v192 offset:34816
	ds_read_b128 v[28:31], v192 offset:35840
	ds_read_b128 v[32:35], v192 offset:36864
	ds_read_b128 v[36:39], v192 offset:37888
	ds_read_b128 v[144:147], v192 offset:38912
	ds_read_b128 v[148:151], v192 offset:39936
	global_load_lds_dwordx4 v[152:153], off
	v_lshl_add_u64 v[152:153], s[36:37], 0, v[162:163]
	s_mov_b32 m0, s65
	s_nop 0
	global_load_lds_dwordx4 v[152:153], off
	s_waitcnt vmcnt(8)
	s_waitcnt lgkmcnt(0)
	s_barrier
; #define PG8_STAGE(bufoff, gbase, voff) do { _Pragma("unroll") for (int _i = 0; _i < 2; ++_i) \
;         __builtin_amdgcn_global_load_lds((const unsigned*)((const char*)(gbase) + (voff)[_i]), (LAS unsigned*)(lds + (bufoff) + ldsw + _i * 8192), 16, 0, 0); } while (0)
; #define PG8_LDA(dst, b, h) do { _Pragma("unroll") for (int m = 0; m < 4; ++m) _Pragma("unroll") for (int k = 0; k < 2; ++k) dst[m][k] = *(const LAS bf16x8*)(lds + PG8_SA(b, h) + aoff + m * 2048 + k * KOFF); } while (0)
; #define PG8_LDB(dst, b, h) do { _Pragma("unroll") for (int n = 0; n < 2; ++n) _Pragma("unroll") for (int k = 0; k < 2; ++k) dst[n][k] = *(const LAS bf16x8*)(lds + PG8_SB(b, h) + boff + n * 2048 + k * KOFF); } while (0)
; #define PG8_WAIT_V(n) asm volatile("s_waitcnt vmcnt(" #n ")" ::: "memory")
; #define PG8_WAIT_L(n) asm volatile("s_waitcnt lgkmcnt(" #n ")" ::: "memory")
; #define PG8_BAR __builtin_amdgcn_s_barrier()
; #define PG8_SCHED __builtin_amdgcn_sched_barrier(0)
; template <class Epi, bool ALIGN_EPI = true, bool FP8 = false>
; __device__ __forceinline__ void gemm_phase(LAS unsigned char* lds, const Gemm g, const StaticOrder& S, const Epi& E, const int wid) {
;     ...
;             PG8_WAIT_V(8); PG8_WAIT_L(0); PG8_BAR; PG8_MMA(1, 0, At, B0); PG8_MMA(1, 1, At, B1); PG8_BAR; PG8_SCHED;
;             PG8_LDB(B0, 1, 0); PG8_LDB(B1, 1, 1); PG8_SCHED; PG8_LDA(At, 1, 0); PG8_STAGE(PG8_SA(0, 1), a2 + hstep, voffA);
;             PG8_WAIT_V(8); PG8_WAIT_L(0); PG8_BAR; PG8_MMA(0, 0, At, B0); PG8_MMA(0, 1, At, B1); PG8_BAR; PG8_SCHED;
;             PG8_LDA(At, 1, 1); PG8_STAGE(PG8_SB(1, 0), b3, voffB); PG8_STAGE(PG8_SB(1, 1), b3 + hstep, voffB); PG8_STAGE(PG8_SA(1, 0), a3, voffA);
;             PG8_WAIT_V(8); PG8_WAIT_L(0); PG8_BAR; PG8_MMA(1, 0, At, B0); PG8_MMA(1, 1, At, B1); PG8_BAR; PG8_SCHED;
	s_setprio 1
	v_mfma_f32_16x16x128_f8f6f4 v[120:123], v[0:7], v[16:23], v[120:123]
	v_mfma_f32_16x16x128_f8f6f4 v[124:127], v[8:15], v[16:23], v[124:127]
	v_mfma_f32_16x16x128_f8f6f4 v[112:115], v[0:7], v[24:31], v[112:115]
	v_mfma_f32_16x16x128_f8f6f4 v[116:119], v[8:15], v[24:31], v[116:119]
	v_mfma_f32_16x16x128_f8f6f4 v[104:107], v[0:7], v[32:39], v[104:107]
	v_mfma_f32_16x16x128_f8f6f4 v[108:111], v[8:15], v[32:39], v[108:111]
	v_mfma_f32_16x16x128_f8f6f4 v[88:91], v[0:7], v[144:151], v[88:91]
	v_mfma_f32_16x16x128_f8f6f4 v[92:95], v[8:15], v[144:151], v[92:95]
	v_mfma_f32_16x16x128_f8f6f4 v[96:99], v[128:135], v[16:23], v[96:99]
	v_mfma_f32_16x16x128_f8f6f4 v[100:103], v[136:143], v[16:23], v[100:103]
	v_mfma_f32_16x16x128_f8f6f4 v[80:83], v[128:135], v[24:31], v[80:83]
	v_mfma_f32_16x16x128_f8f6f4 v[84:87], v[136:143], v[24:31], v[84:87]
	v_mfma_f32_16x16x128_f8f6f4 v[72:75], v[128:135], v[32:39], v[72:75]
	v_mfma_f32_16x16x128_f8f6f4 v[76:79], v[136:143], v[32:39], v[76:79]
	v_mfma_f32_16x16x128_f8f6f4 v[64:67], v[128:135], v[144:151], v[64:67]
	v_mfma_f32_16x16x128_f8f6f4 v[68:71], v[136:143], v[144:151], v[68:71]
	s_setprio 0
	s_barrier
	s_add_i32 s36, s42, s48
	v_lshl_add_u64 v[24:25], v[178:179], 0, s[8:9]
	s_mov_b32 m0, s36
	ds_read_b128 v[16:19], v192 offset:49152
	ds_read_b128 v[20:23], v192 offset:50176
	ds_read_b128 v[144:147], v192 offset:51200
	ds_read_b128 v[148:151], v192 offset:52224
	ds_read_b128 v[152:155], v192 offset:53248
	ds_read_b128 v[156:159], v192 offset:54272
	ds_read_b128 v[196:199], v192 offset:55296
	ds_read_b128 v[200:203], v192 offset:56320
	global_load_lds_dwordx4 v[24:25], off
	s_add_i32 m0, s36, 0x2000
	s_add_u32 s34, s34, 0x40080
	v_lshl_add_u64 v[24:25], v[180:181], 0, s[8:9]
	s_addc_u32 s35, s35, 0
	s_add_i32 s36, s43, s48
	global_load_lds_dwordx4 v[24:25], off
	v_lshl_add_u64 v[24:25], s[34:35], 0, v[164:165]
	s_mov_b32 m0, s36
	s_nop 0
	global_load_lds_dwordx4 v[24:25], off
	v_lshl_add_u64 v[24:25], s[34:35], 0, v[160:161]
	s_add_i32 m0, s36, 0x2000
	s_nop 0
	global_load_lds_dwordx4 v[24:25], off
	v_lshl_add_u64 v[24:25], v[182:183], 0, s[8:9]
	s_mov_b32 m0, s70
	s_nop 0
	global_load_lds_dwordx4 v[24:25], off
	v_lshl_add_u64 v[24:25], v[184:185], 0, s[8:9]
	s_mov_b32 m0, s71
	s_nop 0
	global_load_lds_dwordx4 v[24:25], off
	s_waitcnt vmcnt(8)
	s_waitcnt lgkmcnt(0)
	s_barrier
	s_setprio 1
	v_mfma_f32_16x16x128_f8f6f4 v[56:59], v[0:7], v[16:23], v[56:59]
	v_mfma_f32_16x16x128_f8f6f4 v[60:63], v[8:15], v[16:23], v[60:63]
	v_mfma_f32_16x16x128_f8f6f4 v[48:51], v[0:7], v[144:151], v[48:51]
	v_mfma_f32_16x16x128_f8f6f4 v[52:55], v[8:15], v[144:151], v[52:55]
	v_mfma_f32_16x16x128_f8f6f4 v[40:43], v[0:7], v[152:159], v[40:43]
	v_mfma_f32_16x16x128_f8f6f4 v[44:47], v[8:15], v[152:159], v[44:47]
	v_mfma_f32_16x16x128_f8f6f4 v[24:27], v[0:7], v[196:203], v[228:231]
	v_mfma_f32_16x16x128_f8f6f4 v[28:31], v[8:15], v[196:203], v[232:235]
	v_mfma_f32_16x16x128_f8f6f4 v[32:35], v[128:135], v[16:23], v[236:239]
	v_mfma_f32_16x16x128_f8f6f4 v[36:39], v[136:143], v[16:23], v[240:243]
	v_mfma_f32_16x16x128_f8f6f4 v[16:19], v[128:135], v[144:151], v[244:247]
	v_mfma_f32_16x16x128_f8f6f4 v[20:23], v[136:143], v[144:151], v[204:207]
	v_mfma_f32_16x16x128_f8f6f4 v[8:11], v[128:135], v[152:159], v[208:211]
	v_mfma_f32_16x16x128_f8f6f4 v[12:15], v[136:143], v[152:159], v[212:215]
	v_mfma_f32_16x16x128_f8f6f4 v[0:3], v[128:135], v[196:203], v[216:219]
	v_mfma_f32_16x16x128_f8f6f4 v[4:7], v[136:143], v[196:203], v[220:223]
	s_setprio 0
	s_barrier
	s_add_u32 s30, s30, 0x100
	s_addc_u32 s31, s31, 0
	s_add_u32 s87, s87, 0x100
	s_addc_u32 s88, s88, 0
	s_cmp_ge_u32 s3, s83
	s_mov_b32 s34, s3
	s_cbranch_scc0 .LBB0_572
;     __device__ __forceinline__ void operator()(const Acc& acc, const Unit& u, int wr, int wc, int fr, int fq) const {
;     ...
;                     const size_t ro = (size_t)(ai * HALF + m * 16) * DH;
; #pragma unroll
;                     for (int bj = 0; bj < 2; ++bj) {
;                         const f32x4 v0 = acc[ai][bj][m][0] * QS, v1 = acc[ai][bj][m][1] * QS;
;     ...
;                     const size_t ro = (size_t)(ai * HALF + m * 16) * DM;
; #pragma unroll
;                     for (int bj = 0; bj < 2; ++bj) {
;                         const f32x4 v0 = acc[ai][bj][m][0] * QS, v1 = acc[ai][bj][m][1] * QS;
	v_pk_mul_f32 v[122:123], v[122:123], s[14:15] op_sel_hi:[1,0]
	v_pk_mul_f32 v[128:129], v[120:121], s[14:15] op_sel_hi:[1,0]
	v_pk_mul_f32 v[120:121], v[126:127], s[14:15] op_sel_hi:[1,0]
	v_pk_mul_f32 v[124:125], v[124:125], s[14:15] op_sel_hi:[1,0]
	v_pk_mul_f32 v[132:133], v[98:99], s[14:15] op_sel_hi:[1,0]
	v_pk_mul_f32 v[136:137], v[96:97], s[14:15] op_sel_hi:[1,0]
	v_pk_mul_f32 v[130:131], v[102:103], s[14:15] op_sel_hi:[1,0]
	v_pk_mul_f32 v[134:135], v[100:101], s[14:15] op_sel_hi:[1,0]
	v_pk_mul_f32 v[100:101], v[114:115], s[14:15] op_sel_hi:[1,0]
	v_pk_mul_f32 v[112:113], v[112:113], s[14:15] op_sel_hi:[1,0]
	v_pk_mul_f32 v[96:97], v[118:119], s[14:15] op_sel_hi:[1,0]
	v_pk_mul_f32 v[102:103], v[116:117], s[14:15] op_sel_hi:[1,0]
	v_pk_mul_f32 v[116:117], v[82:83], s[14:15] op_sel_hi:[1,0]
	v_pk_mul_f32 v[126:127], v[80:81], s[14:15] op_sel_hi:[1,0]
	v_pk_mul_f32 v[114:115], v[86:87], s[14:15] op_sel_hi:[1,0]
	v_pk_mul_f32 v[118:119], v[84:85], s[14:15] op_sel_hi:[1,0]
	v_pk_mul_f32 v[82:83], v[106:107], s[14:15] op_sel_hi:[1,0]
	v_pk_mul_f32 v[86:87], v[104:105], s[14:15] op_sel_hi:[1,0]
	v_pk_mul_f32 v[80:81], v[110:111], s[14:15] op_sel_hi:[1,0]
	v_pk_mul_f32 v[84:85], v[108:109], s[14:15] op_sel_hi:[1,0]
	v_pk_mul_f32 v[104:105], v[74:75], s[14:15] op_sel_hi:[1,0]
	v_pk_mul_f32 v[108:109], v[72:73], s[14:15] op_sel_hi:[1,0]
	v_pk_mul_f32 v[98:99], v[78:79], s[14:15] op_sel_hi:[1,0]
	v_pk_mul_f32 v[106:107], v[76:77], s[14:15] op_sel_hi:[1,0]
	v_pk_mul_f32 v[74:75], v[90:91], s[14:15] op_sel_hi:[1,0]
	v_pk_mul_f32 v[78:79], v[88:89], s[14:15] op_sel_hi:[1,0]
	v_pk_mul_f32 v[72:73], v[94:95], s[14:15] op_sel_hi:[1,0]
	v_pk_mul_f32 v[76:77], v[92:93], s[14:15] op_sel_hi:[1,0]
	v_pk_mul_f32 v[66:67], v[66:67], s[14:15] op_sel_hi:[1,0]
	v_pk_mul_f32 v[88:89], v[64:65], s[14:15] op_sel_hi:[1,0]
	v_pk_mul_f32 v[64:65], v[70:71], s[14:15] op_sel_hi:[1,0]
	v_pk_mul_f32 v[68:69], v[68:69], s[14:15] op_sel_hi:[1,0]
	v_pk_mul_f32 v[58:59], v[58:59], s[14:15] op_sel_hi:[1,0]
	v_pk_mul_f32 v[70:71], v[56:57], s[14:15] op_sel_hi:[1,0]
	v_pk_mul_f32 v[56:57], v[62:63], s[14:15] op_sel_hi:[1,0]
	v_pk_mul_f32 v[60:61], v[60:61], s[14:15] op_sel_hi:[1,0]
	v_pk_mul_f32 v[92:93], v[34:35], s[14:15] op_sel_hi:[1,0]
	v_pk_mul_f32 v[110:111], v[32:33], s[14:15] op_sel_hi:[1,0]
	v_pk_mul_f32 v[90:91], v[38:39], s[14:15] op_sel_hi:[1,0]
	v_pk_mul_f32 v[94:95], v[36:37], s[14:15] op_sel_hi:[1,0]
	v_pk_mul_f32 v[36:37], v[50:51], s[14:15] op_sel_hi:[1,0]
	v_pk_mul_f32 v[48:49], v[48:49], s[14:15] op_sel_hi:[1,0]
	v_pk_mul_f32 v[32:33], v[54:55], s[14:15] op_sel_hi:[1,0]
	v_pk_mul_f32 v[38:39], v[52:53], s[14:15] op_sel_hi:[1,0]
	v_pk_mul_f32 v[52:53], v[18:19], s[14:15] op_sel_hi:[1,0]
	v_pk_mul_f32 v[62:63], v[16:17], s[14:15] op_sel_hi:[1,0]
	v_pk_mul_f32 v[50:51], v[22:23], s[14:15] op_sel_hi:[1,0]
	v_pk_mul_f32 v[54:55], v[20:21], s[14:15] op_sel_hi:[1,0]
	v_pk_mul_f32 v[18:19], v[42:43], s[14:15] op_sel_hi:[1,0]
	v_pk_mul_f32 v[22:23], v[40:41], s[14:15] op_sel_hi:[1,0]
	v_pk_mul_f32 v[16:17], v[46:47], s[14:15] op_sel_hi:[1,0]
	v_pk_mul_f32 v[20:21], v[44:45], s[14:15] op_sel_hi:[1,0]
	v_pk_mul_f32 v[40:41], v[10:11], s[14:15] op_sel_hi:[1,0]
	v_pk_mul_f32 v[44:45], v[8:9], s[14:15] op_sel_hi:[1,0]
	v_pk_mul_f32 v[34:35], v[14:15], s[14:15] op_sel_hi:[1,0]
	v_pk_mul_f32 v[42:43], v[12:13], s[14:15] op_sel_hi:[1,0]
	v_pk_mul_f32 v[10:11], v[26:27], s[14:15] op_sel_hi:[1,0]
	v_pk_mul_f32 v[14:15], v[24:25], s[14:15] op_sel_hi:[1,0]
	v_pk_mul_f32 v[8:9], v[30:31], s[14:15] op_sel_hi:[1,0]
	v_pk_mul_f32 v[12:13], v[28:29], s[14:15] op_sel_hi:[1,0]
	v_pk_mul_f32 v[2:3], v[2:3], s[14:15] op_sel_hi:[1,0]
	v_pk_mul_f32 v[24:25], v[0:1], s[14:15] op_sel_hi:[1,0]
	v_pk_mul_f32 v[0:1], v[6:7], s[14:15] op_sel_hi:[1,0]
	v_pk_mul_f32 v[4:5], v[4:5], s[14:15] op_sel_hi:[1,0]
	s_and_b64 vcc, exec, s[12:13]
	s_cbranch_vccz .LBB0_575

; #define PG8_STAGE(bufoff, gbase, voff) do { _Pragma("unroll") for (int _i = 0; _i < 2; ++_i) \
;         __builtin_amdgcn_global_load_lds((const unsigned*)((const char*)(gbase) + (voff)[_i]), (LAS unsigned*)(lds + (bufoff) + ldsw + _i * 8192), 16, 0, 0); } while (0)
; #define PG8_LDA(dst, b, h) do { _Pragma("unroll") for (int m = 0; m < 4; ++m) _Pragma("unroll") for (int k = 0; k < 2; ++k) dst[m][k] = *(const LAS bf16x8*)(lds + PG8_SA(b, h) + aoff + m * 2048 + k * KOFF); } while (0)
; #define PG8_LDB(dst, b, h) do { _Pragma("unroll") for (int n = 0; n < 2; ++n) _Pragma("unroll") for (int k = 0; k < 2; ++k) dst[n][k] = *(const LAS bf16x8*)(lds + PG8_SB(b, h) + boff + n * 2048 + k * KOFF); } while (0)
; #define PG8_WAIT_V(n) asm volatile("s_waitcnt vmcnt(" #n ")" ::: "memory")
; #define PG8_WAIT_L(n) asm volatile("s_waitcnt lgkmcnt(" #n ")" ::: "memory")
; #define PG8_BAR __builtin_amdgcn_s_barrier()
; #define PG8_SCHED __builtin_amdgcn_sched_barrier(0)
; template <class Epi, bool ALIGN_EPI = true, bool FP8 = false>
; __device__ __forceinline__ void gemm_phase(LAS unsigned char* lds, const Gemm g, const StaticOrder& S, const Epi& E, const int wid) {
;     ...
;             PG8_LDB(B0, 0, 0); PG8_LDB(B1, 0, 1); PG8_SCHED; PG8_LDA(At, 0, 0); PG8_STAGE(PG8_SA(1, 1), a1 + hstep, voffA);
;             PG8_WAIT_V(8); PG8_WAIT_L(0); PG8_BAR; PG8_MMA(0, 0, At, B0); PG8_MMA(0, 1, At, B1); PG8_BAR; PG8_SCHED;
;             PG8_LDA(At, 0, 1); PG8_STAGE(PG8_SB(0, 0), b2, voffB); PG8_STAGE(PG8_SB(0, 1), b2 + hstep, voffB); PG8_STAGE(PG8_SA(0, 0), a2, voffA);
;             PG8_WAIT_V(8); PG8_WAIT_L(0); PG8_BAR; PG8_MMA(1, 0, At, B0); PG8_MMA(1, 1, At, B1); PG8_BAR; PG8_SCHED;
.LBB0_2058:
	v_add_u32_e32 v128, s83, v192
	v_add_u32_e32 v132, s84, v192
	ds_read_b128 v[152:155], v128
	ds_read_b128 v[156:159], v128 offset:1024
	ds_read_b128 v[144:147], v128 offset:2048
	ds_read_b128 v[148:151], v128 offset:3072
	ds_read_b128 v[136:139], v132
	ds_read_b128 v[140:143], v132 offset:1024
	ds_read_b128 v[128:131], v132 offset:2048
	ds_read_b128 v[132:135], v132 offset:3072
	s_add_i32 s3, s42, 2
	s_add_u32 s43, s64, 0xfffe0080
	s_addc_u32 s52, s65, -1
	s_cmp_eq_u32 s35, s42
	s_cselect_b32 s69, s11, s52
	s_cselect_b32 s68, s16, s43
	s_cselect_b32 s67, s29, s90
	s_cselect_b32 s66, s31, s89
	v_lshl_add_u64 v[188:189], s[64:65], 0, v[174:175]
	s_add_i32 m0, s72, 0xc000
	ds_read_b128 v[180:183], v193
	ds_read_b128 v[184:187], v193 offset:1024
	ds_read_b128 v[196:199], v193 offset:2048
	ds_read_b128 v[200:203], v193 offset:3072
	ds_read_b128 v[204:207], v193 offset:4096
	ds_read_b128 v[208:211], v193 offset:5120
	ds_read_b128 v[212:215], v193 offset:6144
	ds_read_b128 v[216:219], v193 offset:7168
	global_load_lds_dwordx4 v[188:189], off
	v_lshl_add_u64 v[188:189], s[64:65], 0, v[176:177]
	s_add_i32 m0, s72, 0xe000
	s_nop 0
	global_load_lds_dwordx4 v[188:189], off
	s_waitcnt vmcnt(8)
	s_waitcnt lgkmcnt(0)
	s_barrier
	s_setprio 1
	v_mfma_f32_16x16x128_f8f6f4 v[120:123], v[152:159], v[180:187], v[120:123]
	v_mfma_f32_16x16x128_f8f6f4 v[124:127], v[144:151], v[180:187], v[124:127]
	v_mfma_f32_16x16x128_f8f6f4 v[112:115], v[152:159], v[196:203], v[112:115]
	v_mfma_f32_16x16x128_f8f6f4 v[116:119], v[144:151], v[196:203], v[116:119]
	v_mfma_f32_16x16x128_f8f6f4 v[104:107], v[152:159], v[204:211], v[104:107]
	v_mfma_f32_16x16x128_f8f6f4 v[108:111], v[144:151], v[204:211], v[108:111]
	v_mfma_f32_16x16x128_f8f6f4 v[96:99], v[152:159], v[212:219], v[96:99]
	v_mfma_f32_16x16x128_f8f6f4 v[100:103], v[144:151], v[212:219], v[100:103]
	v_mfma_f32_16x16x128_f8f6f4 v[88:91], v[136:143], v[180:187], v[88:91]
	v_mfma_f32_16x16x128_f8f6f4 v[92:95], v[128:135], v[180:187], v[92:95]
	v_mfma_f32_16x16x128_f8f6f4 v[80:83], v[136:143], v[196:203], v[80:83]
	v_mfma_f32_16x16x128_f8f6f4 v[84:87], v[128:135], v[196:203], v[84:87]
	v_mfma_f32_16x16x128_f8f6f4 v[72:75], v[136:143], v[204:211], v[72:75]
	v_mfma_f32_16x16x128_f8f6f4 v[76:79], v[128:135], v[204:211], v[76:79]
	v_mfma_f32_16x16x128_f8f6f4 v[64:67], v[136:143], v[212:219], v[64:67]
	v_mfma_f32_16x16x128_f8f6f4 v[68:71], v[128:135], v[212:219], v[68:71]
	s_setprio 0
	s_barrier
	s_add_i32 s42, s83, s71
	v_lshl_add_u64 v[180:181], s[66:67], 0, v[162:163]
	s_mov_b32 m0, s42
	ds_read_b128 v[196:199], v193 offset:16384
	ds_read_b128 v[200:203], v193 offset:17408
	ds_read_b128 v[204:207], v193 offset:18432
	ds_read_b128 v[208:211], v193 offset:19456
	ds_read_b128 v[212:215], v193 offset:20480
	ds_read_b128 v[216:219], v193 offset:21504
	ds_read_b128 v[220:223], v193 offset:22528
	ds_read_b128 v[224:227], v193 offset:23552
	global_load_lds_dwordx4 v[180:181], off
	s_add_i32 m0, s42, 0x2000
	s_add_u32 s42, s66, 0x20000
	v_lshl_add_u64 v[182:183], s[66:67], 0, v[166:167]
	s_addc_u32 s43, s67, 0
	s_add_i32 s52, s84, s71
	global_load_lds_dwordx4 v[182:183], off
	v_lshl_add_u64 v[184:185], s[42:43], 0, v[162:163]
	s_mov_b32 m0, s52
	v_lshl_add_u64 v[186:187], s[68:69], 0, v[164:165]
	global_load_lds_dwordx4 v[184:185], off
	v_lshl_add_u64 v[184:185], s[42:43], 0, v[166:167]
	s_add_i32 m0, s52, 0x2000
	s_nop 0
	global_load_lds_dwordx4 v[184:185], off
	v_lshl_add_u64 v[184:185], s[68:69], 0, v[160:161]
	s_mov_b32 m0, s72
	s_nop 0
	global_load_lds_dwordx4 v[184:185], off
	s_mov_b32 m0, s73
	s_nop 0
	global_load_lds_dwordx4 v[186:187], off
	s_waitcnt vmcnt(8)
	s_waitcnt lgkmcnt(0)
	s_barrier
	s_setprio 1
	v_mfma_f32_16x16x128_f8f6f4 v[56:59], v[152:159], v[196:203], v[56:59]
	v_mfma_f32_16x16x128_f8f6f4 v[60:63], v[144:151], v[196:203], v[60:63]
	v_mfma_f32_16x16x128_f8f6f4 v[48:51], v[152:159], v[204:211], v[48:51]
	v_mfma_f32_16x16x128_f8f6f4 v[52:55], v[144:151], v[204:211], v[52:55]
	v_mfma_f32_16x16x128_f8f6f4 v[40:43], v[152:159], v[212:219], v[40:43]
	v_mfma_f32_16x16x128_f8f6f4 v[44:47], v[144:151], v[212:219], v[44:47]
	v_mfma_f32_16x16x128_f8f6f4 v[188:191], v[152:159], v[220:227], v[32:35]
	v_mfma_f32_16x16x128_f8f6f4 v[228:231], v[144:151], v[220:227], v[36:39]
	v_mfma_f32_16x16x128_f8f6f4 v[232:235], v[136:143], v[196:203], v[24:27]
	v_mfma_f32_16x16x128_f8f6f4 v[236:239], v[128:135], v[196:203], v[28:31]
	v_mfma_f32_16x16x128_f8f6f4 v[240:243], v[136:143], v[204:211], v[16:19]
	v_mfma_f32_16x16x128_f8f6f4 v[204:207], v[128:135], v[204:211], v[20:23]
	v_mfma_f32_16x16x128_f8f6f4 v[208:211], v[136:143], v[212:219], v[8:11]
	v_mfma_f32_16x16x128_f8f6f4 v[212:215], v[128:135], v[212:219], v[12:15]
	v_mfma_f32_16x16x128_f8f6f4 v[216:219], v[136:143], v[220:227], v[0:3]
	v_mfma_f32_16x16x128_f8f6f4 v[220:223], v[128:135], v[220:227], v[4:7]
	s_setprio 0
	s_barrier
; #define PG8_STAGE(bufoff, gbase, voff) do { _Pragma("unroll") for (int _i = 0; _i < 2; ++_i) \
;         __builtin_amdgcn_global_load_lds((const unsigned*)((const char*)(gbase) + (voff)[_i]), (LAS unsigned*)(lds + (bufoff) + ldsw + _i * 8192), 16, 0, 0); } while (0)
; #define PG8_LDA(dst, b, h) do { _Pragma("unroll") for (int m = 0; m < 4; ++m) _Pragma("unroll") for (int k = 0; k < 2; ++k) dst[m][k] = *(const LAS bf16x8*)(lds + PG8_SA(b, h) + aoff + m * 2048 + k * KOFF); } while (0)
; #define PG8_LDB(dst, b, h) do { _Pragma("unroll") for (int n = 0; n < 2; ++n) _Pragma("unroll") for (int k = 0; k < 2; ++k) dst[n][k] = *(const LAS bf16x8*)(lds + PG8_SB(b, h) + boff + n * 2048 + k * KOFF); } while (0)
; #define PG8_WAIT_V(n) asm volatile("s_waitcnt vmcnt(" #n ")" ::: "memory")
; #define PG8_WAIT_L(n) asm volatile("s_waitcnt lgkmcnt(" #n ")" ::: "memory")
; #define PG8_BAR __builtin_amdgcn_s_barrier()
; #define PG8_SCHED __builtin_amdgcn_sched_barrier(0)
; template <class Epi, bool ALIGN_EPI = true, bool FP8 = false>
; __device__ __forceinline__ void gemm_phase(LAS unsigned char* lds, const Gemm g, const StaticOrder& S, const Epi& E, const int wid) {
;     ...
;             PG8_LDB(B0, 1, 0); PG8_LDB(B1, 1, 1); PG8_SCHED; PG8_LDA(At, 1, 0); PG8_STAGE(PG8_SA(0, 1), a2 + hstep, voffA);
;             PG8_WAIT_V(8); PG8_WAIT_L(0); PG8_BAR; PG8_MMA(0, 0, At, B0); PG8_MMA(0, 1, At, B1); PG8_BAR; PG8_SCHED;
;             PG8_LDA(At, 1, 1); PG8_STAGE(PG8_SB(1, 0), b3, voffB); PG8_STAGE(PG8_SB(1, 1), b3 + hstep, voffB); PG8_STAGE(PG8_SA(1, 0), a3, voffA);
;             PG8_WAIT_V(8); PG8_WAIT_L(0); PG8_BAR; PG8_MMA(1, 0, At, B0); PG8_MMA(1, 1, At, B1); PG8_BAR; PG8_SCHED;
;         }
	s_add_i32 s52, 0, 0x18000
	s_add_i32 s54, 0, 0x1c000
	s_nop 0
	v_add_u32_e32 v12, s52, v192
	v_add_u32_e32 v16, s54, v192
	ds_read_b128 v[0:3], v12
	ds_read_b128 v[4:7], v12 offset:1024
	ds_read_b128 v[8:11], v12 offset:2048
	ds_read_b128 v[12:15], v12 offset:3072
	ds_read_b128 v[128:131], v16
	ds_read_b128 v[132:135], v16 offset:1024
	ds_read_b128 v[136:139], v16 offset:2048
	ds_read_b128 v[140:143], v16 offset:3072
	s_add_u32 s42, s68, 0x20000
	s_addc_u32 s43, s69, 0
	s_mov_b32 m0, s74
	v_lshl_add_u64 v[152:153], s[42:43], 0, v[160:161]
	ds_read_b128 v[16:19], v193 offset:32768
	ds_read_b128 v[20:23], v193 offset:33792
	ds_read_b128 v[24:27], v193 offset:34816
	ds_read_b128 v[28:31], v193 offset:35840
	ds_read_b128 v[32:35], v193 offset:36864
	ds_read_b128 v[36:39], v193 offset:37888
	ds_read_b128 v[144:147], v193 offset:38912
	ds_read_b128 v[148:151], v193 offset:39936
	global_load_lds_dwordx4 v[152:153], off
	v_lshl_add_u64 v[152:153], s[42:43], 0, v[164:165]
	s_mov_b32 m0, s75
	s_nop 0
	global_load_lds_dwordx4 v[152:153], off
	s_waitcnt vmcnt(8)
	s_waitcnt lgkmcnt(0)
	s_barrier
	s_setprio 1
	v_mfma_f32_16x16x128_f8f6f4 v[120:123], v[0:7], v[16:23], v[120:123]
	v_mfma_f32_16x16x128_f8f6f4 v[124:127], v[8:15], v[16:23], v[124:127]
	v_mfma_f32_16x16x128_f8f6f4 v[112:115], v[0:7], v[24:31], v[112:115]
	v_mfma_f32_16x16x128_f8f6f4 v[116:119], v[8:15], v[24:31], v[116:119]
	v_mfma_f32_16x16x128_f8f6f4 v[104:107], v[0:7], v[32:39], v[104:107]
	v_mfma_f32_16x16x128_f8f6f4 v[108:111], v[8:15], v[32:39], v[108:111]
	v_mfma_f32_16x16x128_f8f6f4 v[96:99], v[0:7], v[144:151], v[96:99]
	v_mfma_f32_16x16x128_f8f6f4 v[100:103], v[8:15], v[144:151], v[100:103]
	v_mfma_f32_16x16x128_f8f6f4 v[88:91], v[128:135], v[16:23], v[88:91]
	v_mfma_f32_16x16x128_f8f6f4 v[92:95], v[136:143], v[16:23], v[92:95]
	v_mfma_f32_16x16x128_f8f6f4 v[80:83], v[128:135], v[24:31], v[80:83]
	v_mfma_f32_16x16x128_f8f6f4 v[84:87], v[136:143], v[24:31], v[84:87]
	v_mfma_f32_16x16x128_f8f6f4 v[72:75], v[128:135], v[32:39], v[72:75]
	v_mfma_f32_16x16x128_f8f6f4 v[76:79], v[136:143], v[32:39], v[76:79]
	v_mfma_f32_16x16x128_f8f6f4 v[64:67], v[128:135], v[144:151], v[64:67]
	v_mfma_f32_16x16x128_f8f6f4 v[68:71], v[136:143], v[144:151], v[68:71]
	s_setprio 0
	s_barrier
	s_add_i32 s42, s52, s71
	v_lshl_add_u64 v[24:25], v[180:181], 0, s[20:21]
	s_mov_b32 m0, s42
	ds_read_b128 v[16:19], v193 offset:49152
	ds_read_b128 v[20:23], v193 offset:50176
	ds_read_b128 v[144:147], v193 offset:51200
	ds_read_b128 v[148:151], v193 offset:52224
	ds_read_b128 v[152:155], v193 offset:53248
	ds_read_b128 v[156:159], v193 offset:54272
	ds_read_b128 v[196:199], v193 offset:55296
	ds_read_b128 v[200:203], v193 offset:56320
	global_load_lds_dwordx4 v[24:25], off
	s_add_i32 m0, s42, 0x2000
	s_add_u32 s42, s66, 0x20080
	v_lshl_add_u64 v[24:25], v[182:183], 0, s[20:21]
	s_addc_u32 s43, s67, 0
	s_add_i32 s52, s54, s71
	global_load_lds_dwordx4 v[24:25], off
	v_lshl_add_u64 v[24:25], s[42:43], 0, v[162:163]
	s_mov_b32 m0, s52
	s_nop 0
	global_load_lds_dwordx4 v[24:25], off
	v_lshl_add_u64 v[24:25], s[42:43], 0, v[166:167]
	s_add_i32 m0, s52, 0x2000
	s_nop 0
	global_load_lds_dwordx4 v[24:25], off
	v_lshl_add_u64 v[24:25], v[184:185], 0, s[20:21]
	s_mov_b32 m0, s80
	s_nop 0
	global_load_lds_dwordx4 v[24:25], off
	v_lshl_add_u64 v[24:25], v[186:187], 0, s[20:21]
	s_mov_b32 m0, s81
	s_nop 0
	global_load_lds_dwordx4 v[24:25], off
	s_waitcnt vmcnt(8)
	s_waitcnt lgkmcnt(0)
	s_barrier
	s_setprio 1
	v_mfma_f32_16x16x128_f8f6f4 v[56:59], v[0:7], v[16:23], v[56:59]
	v_mfma_f32_16x16x128_f8f6f4 v[60:63], v[8:15], v[16:23], v[60:63]
	v_mfma_f32_16x16x128_f8f6f4 v[48:51], v[0:7], v[144:151], v[48:51]
	v_mfma_f32_16x16x128_f8f6f4 v[52:55], v[8:15], v[144:151], v[52:55]
	v_mfma_f32_16x16x128_f8f6f4 v[40:43], v[0:7], v[152:159], v[40:43]
	v_mfma_f32_16x16x128_f8f6f4 v[44:47], v[8:15], v[152:159], v[44:47]
	v_mfma_f32_16x16x128_f8f6f4 v[32:35], v[0:7], v[196:203], v[188:191]
	v_mfma_f32_16x16x128_f8f6f4 v[36:39], v[8:15], v[196:203], v[228:231]
	v_mfma_f32_16x16x128_f8f6f4 v[24:27], v[128:135], v[16:23], v[232:235]
	v_mfma_f32_16x16x128_f8f6f4 v[28:31], v[136:143], v[16:23], v[236:239]
	v_mfma_f32_16x16x128_f8f6f4 v[16:19], v[128:135], v[144:151], v[240:243]
	v_mfma_f32_16x16x128_f8f6f4 v[20:23], v[136:143], v[144:151], v[204:207]
	v_mfma_f32_16x16x128_f8f6f4 v[8:11], v[128:135], v[152:159], v[208:211]
	v_mfma_f32_16x16x128_f8f6f4 v[12:15], v[136:143], v[152:159], v[212:215]
	v_mfma_f32_16x16x128_f8f6f4 v[0:3], v[128:135], v[196:203], v[216:219]
	v_mfma_f32_16x16x128_f8f6f4 v[4:7], v[136:143], v[196:203], v[220:223]
	s_setprio 0
	s_barrier
	s_add_u32 s64, s64, 0x100
	s_addc_u32 s65, s65, 0
	s_add_u32 s89, s89, 0x100
	s_addc_u32 s90, s90, 0
	s_cmp_ge_u32 s3, s9
	s_mov_b32 s42, s3
	s_cbranch_scc0 .LBB0_2058
	s_and_b64 vcc, exec, s[22:23]
	s_cbranch_vccz .LBB0_2061
	s_barrier

; #define PG8_STAGE(bufoff, gbase, voff) do { _Pragma("unroll") for (int _i = 0; _i < 2; ++_i) \
;         __builtin_amdgcn_global_load_lds((const unsigned*)((const char*)(gbase) + (voff)[_i]), (LAS unsigned*)(lds + (bufoff) + ldsw + _i * 8192), 16, 0, 0); } while (0)
; #define PG8_LDA(dst, b, h) do { _Pragma("unroll") for (int m = 0; m < 4; ++m) _Pragma("unroll") for (int k = 0; k < 2; ++k) dst[m][k] = *(const LAS bf16x8*)(lds + PG8_SA(b, h) + aoff + m * 2048 + k * KOFF); } while (0)
; #define PG8_LDB(dst, b, h) do { _Pragma("unroll") for (int n = 0; n < 2; ++n) _Pragma("unroll") for (int k = 0; k < 2; ++k) dst[n][k] = *(const LAS bf16x8*)(lds + PG8_SB(b, h) + boff + n * 2048 + k * KOFF); } while (0)
; #define PG8_WAIT_V(n) asm volatile("s_waitcnt vmcnt(" #n ")" ::: "memory")
; #define PG8_WAIT_L(n) asm volatile("s_waitcnt lgkmcnt(" #n ")" ::: "memory")
; #define PG8_BAR __builtin_amdgcn_s_barrier()
; #define PG8_SCHED __builtin_amdgcn_sched_barrier(0)
; template <class Epi, bool ALIGN_EPI = true, bool FP8 = false>
; __device__ __forceinline__ void gemm_phase(LAS unsigned char* lds, const Gemm g, const StaticOrder& S, const Epi& E, const int wid) {
;     ...
;             PG8_LDB(B0, 0, 0); PG8_LDB(B1, 0, 1); PG8_SCHED; PG8_LDA(At, 0, 0); PG8_STAGE(PG8_SA(1, 1), a1 + hstep, voffA);
;             PG8_WAIT_V(8); PG8_WAIT_L(0); PG8_BAR; PG8_MMA(0, 0, At, B0); PG8_MMA(0, 1, At, B1); PG8_BAR; PG8_SCHED;
;             PG8_LDA(At, 0, 1); PG8_STAGE(PG8_SB(0, 0), b2, voffB); PG8_STAGE(PG8_SB(0, 1), b2 + hstep, voffB); PG8_STAGE(PG8_SA(0, 0), a2, voffA);
;             PG8_WAIT_V(8); PG8_WAIT_L(0); PG8_BAR; PG8_MMA(1, 0, At, B0); PG8_MMA(1, 1, At, B1); PG8_BAR; PG8_SCHED;
.LBB0_2290:
	ds_read_b128 v[152:155], v218
	ds_read_b128 v[156:159], v218 offset:1024
	ds_read_b128 v[144:147], v218 offset:2048
	ds_read_b128 v[148:151], v218 offset:3072
	ds_read_b128 v[136:139], v219
	ds_read_b128 v[140:143], v219 offset:1024
	ds_read_b128 v[128:131], v219 offset:2048
	ds_read_b128 v[132:135], v219 offset:3072
	s_add_i32 s3, s38, 2
	s_add_u32 s36, s34, 0xfffc0080
	s_addc_u32 s37, s35, -1
	s_cmp_eq_u32 s88, s38
	s_cselect_b32 s38, s31, s36
	s_cselect_b32 s39, s21, s37
	s_cselect_b32 s37, s19, s90
	s_cselect_b32 s36, s87, s89
	v_lshl_add_u64 v[212:213], s[34:35], 0, v[198:199]
	s_add_i32 m0, s27, 0xc000
	ds_read_b128 v[160:163], v220
	ds_read_b128 v[164:167], v220 offset:1024
	ds_read_b128 v[168:171], v220 offset:2048
	ds_read_b128 v[172:175], v220 offset:3072
	ds_read_b128 v[176:179], v220 offset:4096
	ds_read_b128 v[180:183], v220 offset:5120
	ds_read_b128 v[204:207], v220 offset:6144
	ds_read_b128 v[208:211], v220 offset:7168
	global_load_lds_dwordx4 v[212:213], off
	v_lshl_add_u64 v[212:213], s[34:35], 0, v[200:201]
	s_add_i32 m0, s27, 0xe000
	s_nop 0
	global_load_lds_dwordx4 v[212:213], off
	s_waitcnt vmcnt(8)
	s_waitcnt lgkmcnt(0)
	s_barrier
	s_setprio 1
	v_mfma_f32_16x16x128_f8f6f4 v[120:123], v[152:159], v[160:167], v[120:123]
	v_mfma_f32_16x16x128_f8f6f4 v[124:127], v[144:151], v[160:167], v[124:127]
	v_mfma_f32_16x16x128_f8f6f4 v[104:107], v[152:159], v[168:175], v[104:107]
	v_mfma_f32_16x16x128_f8f6f4 v[108:111], v[144:151], v[168:175], v[108:111]
	v_mfma_f32_16x16x128_f8f6f4 v[96:99], v[152:159], v[176:183], v[96:99]
	v_mfma_f32_16x16x128_f8f6f4 v[100:103], v[144:151], v[176:183], v[100:103]
	v_mfma_f32_16x16x128_f8f6f4 v[80:83], v[152:159], v[204:211], v[80:83]
	v_mfma_f32_16x16x128_f8f6f4 v[84:87], v[144:151], v[204:211], v[84:87]
	v_mfma_f32_16x16x128_f8f6f4 v[112:115], v[136:143], v[160:167], v[112:115]
	v_mfma_f32_16x16x128_f8f6f4 v[116:119], v[128:135], v[160:167], v[116:119]
	v_mfma_f32_16x16x128_f8f6f4 v[88:91], v[136:143], v[168:175], v[88:91]
	v_mfma_f32_16x16x128_f8f6f4 v[92:95], v[128:135], v[168:175], v[92:95]
	v_mfma_f32_16x16x128_f8f6f4 v[72:75], v[136:143], v[176:183], v[72:75]
	v_mfma_f32_16x16x128_f8f6f4 v[76:79], v[128:135], v[176:183], v[76:79]
	v_mfma_f32_16x16x128_f8f6f4 v[64:67], v[136:143], v[204:211], v[64:67]
	v_mfma_f32_16x16x128_f8f6f4 v[68:71], v[128:135], v[204:211], v[68:71]
	s_setprio 0
	s_barrier
	s_add_i32 s42, s75, s53
	v_lshl_add_u64 v[160:161], s[36:37], 0, v[188:189]
	s_mov_b32 m0, s42
	ds_read_b128 v[168:171], v220 offset:16384
	ds_read_b128 v[172:175], v220 offset:17408
	ds_read_b128 v[176:179], v220 offset:18432
	ds_read_b128 v[180:183], v220 offset:19456
	ds_read_b128 v[204:207], v220 offset:20480
	ds_read_b128 v[208:211], v220 offset:21504
	ds_read_b128 v[222:225], v220 offset:22528
	ds_read_b128 v[226:229], v220 offset:23552
	global_load_lds_dwordx4 v[160:161], off
	s_add_i32 m0, s42, 0x2000
	s_add_u32 s42, s36, 0x40000
	v_lshl_add_u64 v[162:163], s[36:37], 0, v[184:185]
	s_addc_u32 s43, s37, 0
	s_add_i32 s52, s76, s53
	global_load_lds_dwordx4 v[162:163], off
	v_lshl_add_u64 v[164:165], s[42:43], 0, v[188:189]
	s_mov_b32 m0, s52
	v_lshl_add_u64 v[166:167], s[38:39], 0, v[186:187]
	global_load_lds_dwordx4 v[164:165], off
	v_lshl_add_u64 v[164:165], s[42:43], 0, v[184:185]
	s_add_i32 m0, s52, 0x2000
	s_nop 0
	global_load_lds_dwordx4 v[164:165], off
	v_lshl_add_u64 v[164:165], s[38:39], 0, v[190:191]
	s_mov_b32 m0, s27
	s_nop 0
	global_load_lds_dwordx4 v[164:165], off
	s_mov_b32 m0, s55
	s_nop 0
	global_load_lds_dwordx4 v[166:167], off
	s_waitcnt vmcnt(8)
	s_waitcnt lgkmcnt(0)
	s_barrier
	s_setprio 1
	v_mfma_f32_16x16x128_f8f6f4 v[56:59], v[152:159], v[168:175], v[56:59]
	v_mfma_f32_16x16x128_f8f6f4 v[60:63], v[144:151], v[168:175], v[60:63]
	v_mfma_f32_16x16x128_f8f6f4 v[48:51], v[152:159], v[176:183], v[48:51]
	v_mfma_f32_16x16x128_f8f6f4 v[52:55], v[144:151], v[176:183], v[52:55]
	v_mfma_f32_16x16x128_f8f6f4 v[32:35], v[152:159], v[204:211], v[32:35]
	v_mfma_f32_16x16x128_f8f6f4 v[212:215], v[144:151], v[204:211], v[36:39]
	v_mfma_f32_16x16x128_f8f6f4 v[230:233], v[152:159], v[222:229], v[16:19]
	v_mfma_f32_16x16x128_f8f6f4 v[234:237], v[144:151], v[222:229], v[20:23]
	v_mfma_f32_16x16x128_f8f6f4 v[44:47], v[128:135], v[168:175], v[44:47]
	v_mfma_f32_16x16x128_f8f6f4 v[238:241], v[136:143], v[168:175], v[40:43]
	v_mfma_f32_16x16x128_f8f6f4 v[242:245], v[136:143], v[176:183], v[24:27]
	v_mfma_f32_16x16x128_f8f6f4 v[176:179], v[128:135], v[176:183], v[28:31]
	v_mfma_f32_16x16x128_f8f6f4 v[180:183], v[136:143], v[204:211], v[8:11]
	v_mfma_f32_16x16x128_f8f6f4 v[204:207], v[128:135], v[204:211], v[12:15]
	v_mfma_f32_16x16x128_f8f6f4 v[208:211], v[136:143], v[222:229], v[0:3]
	v_mfma_f32_16x16x128_f8f6f4 v[222:225], v[128:135], v[222:229], v[4:7]
	s_setprio 0
	s_barrier
; #define PG8_STAGE(bufoff, gbase, voff) do { _Pragma("unroll") for (int _i = 0; _i < 2; ++_i) \
;         __builtin_amdgcn_global_load_lds((const unsigned*)((const char*)(gbase) + (voff)[_i]), (LAS unsigned*)(lds + (bufoff) + ldsw + _i * 8192), 16, 0, 0); } while (0)
; #define PG8_LDA(dst, b, h) do { _Pragma("unroll") for (int m = 0; m < 4; ++m) _Pragma("unroll") for (int k = 0; k < 2; ++k) dst[m][k] = *(const LAS bf16x8*)(lds + PG8_SA(b, h) + aoff + m * 2048 + k * KOFF); } while (0)
; #define PG8_LDB(dst, b, h) do { _Pragma("unroll") for (int n = 0; n < 2; ++n) _Pragma("unroll") for (int k = 0; k < 2; ++k) dst[n][k] = *(const LAS bf16x8*)(lds + PG8_SB(b, h) + boff + n * 2048 + k * KOFF); } while (0)
; #define PG8_WAIT_V(n) asm volatile("s_waitcnt vmcnt(" #n ")" ::: "memory")
; #define PG8_WAIT_L(n) asm volatile("s_waitcnt lgkmcnt(" #n ")" ::: "memory")
; #define PG8_BAR __builtin_amdgcn_s_barrier()
; #define PG8_SCHED __builtin_amdgcn_sched_barrier(0)
; template <class Epi, bool ALIGN_EPI = true, bool FP8 = false>
; __device__ __forceinline__ void gemm_phase(LAS unsigned char* lds, const Gemm g, const StaticOrder& S, const Epi& E, const int wid) {
;     ...
;             PG8_LDB(B0, 1, 0); PG8_LDB(B1, 1, 1); PG8_SCHED; PG8_LDA(At, 1, 0); PG8_STAGE(PG8_SA(0, 1), a2 + hstep, voffA);
;             PG8_WAIT_V(8); PG8_WAIT_L(0); PG8_BAR; PG8_MMA(0, 0, At, B0); PG8_MMA(0, 1, At, B1); PG8_BAR; PG8_SCHED;
;             PG8_LDA(At, 1, 1); PG8_STAGE(PG8_SB(1, 0), b3, voffB); PG8_STAGE(PG8_SB(1, 1), b3 + hstep, voffB); PG8_STAGE(PG8_SA(1, 0), a3, voffA);
;             PG8_WAIT_V(8); PG8_WAIT_L(0); PG8_BAR; PG8_MMA(1, 0, At, B0); PG8_MMA(1, 1, At, B1); PG8_BAR; PG8_SCHED;
;         }
	s_add_i32 s42, 0, 0x18000
	s_add_i32 s43, 0, 0x1c000
	s_nop 0
	v_add_u32_e32 v12, s42, v217
	v_add_u32_e32 v16, s43, v217
	ds_read_b128 v[0:3], v12
	ds_read_b128 v[4:7], v12 offset:1024
	ds_read_b128 v[8:11], v12 offset:2048
	ds_read_b128 v[12:15], v12 offset:3072
	ds_read_b128 v[128:131], v16
	ds_read_b128 v[132:135], v16 offset:1024
	ds_read_b128 v[136:139], v16 offset:2048
	ds_read_b128 v[140:143], v16 offset:3072
	s_add_u32 s38, s38, 0x40000
	s_addc_u32 s39, s39, 0
	s_mov_b32 m0, s64
	v_lshl_add_u64 v[152:153], s[38:39], 0, v[190:191]
	ds_read_b128 v[16:19], v220 offset:32768
	ds_read_b128 v[20:23], v220 offset:33792
	ds_read_b128 v[24:27], v220 offset:34816
	ds_read_b128 v[28:31], v220 offset:35840
	ds_read_b128 v[36:39], v220 offset:36864
	ds_read_b128 v[40:43], v220 offset:37888
	ds_read_b128 v[144:147], v220 offset:38912
	ds_read_b128 v[148:151], v220 offset:39936
	global_load_lds_dwordx4 v[152:153], off
	v_lshl_add_u64 v[152:153], s[38:39], 0, v[186:187]
	s_mov_b32 m0, s65
	s_nop 0
	global_load_lds_dwordx4 v[152:153], off
	s_waitcnt vmcnt(8)
	s_waitcnt lgkmcnt(0)
	s_barrier
	s_setprio 1
	v_mfma_f32_16x16x128_f8f6f4 v[120:123], v[0:7], v[16:23], v[120:123]
	v_mfma_f32_16x16x128_f8f6f4 v[124:127], v[8:15], v[16:23], v[124:127]
	v_mfma_f32_16x16x128_f8f6f4 v[104:107], v[0:7], v[24:31], v[104:107]
	v_mfma_f32_16x16x128_f8f6f4 v[108:111], v[8:15], v[24:31], v[108:111]
	v_mfma_f32_16x16x128_f8f6f4 v[96:99], v[0:7], v[36:43], v[96:99]
	v_mfma_f32_16x16x128_f8f6f4 v[100:103], v[8:15], v[36:43], v[100:103]
	v_mfma_f32_16x16x128_f8f6f4 v[80:83], v[0:7], v[144:151], v[80:83]
	v_mfma_f32_16x16x128_f8f6f4 v[84:87], v[8:15], v[144:151], v[84:87]
	v_mfma_f32_16x16x128_f8f6f4 v[112:115], v[128:135], v[16:23], v[112:115]
	v_mfma_f32_16x16x128_f8f6f4 v[116:119], v[136:143], v[16:23], v[116:119]
	v_mfma_f32_16x16x128_f8f6f4 v[88:91], v[128:135], v[24:31], v[88:91]
	v_mfma_f32_16x16x128_f8f6f4 v[92:95], v[136:143], v[24:31], v[92:95]
	v_mfma_f32_16x16x128_f8f6f4 v[72:75], v[128:135], v[36:43], v[72:75]
	v_mfma_f32_16x16x128_f8f6f4 v[76:79], v[136:143], v[36:43], v[76:79]
	v_mfma_f32_16x16x128_f8f6f4 v[64:67], v[128:135], v[144:151], v[64:67]
	v_mfma_f32_16x16x128_f8f6f4 v[68:71], v[136:143], v[144:151], v[68:71]
	s_setprio 0
	s_barrier
	s_add_i32 s38, s42, s53
	v_lshl_add_u64 v[16:17], v[160:161], 0, s[14:15]
	s_mov_b32 m0, s38
	ds_read_b128 v[24:27], v220 offset:49152
	ds_read_b128 v[28:31], v220 offset:50176
	ds_read_b128 v[144:147], v220 offset:51200
	ds_read_b128 v[148:151], v220 offset:52224
	ds_read_b128 v[152:155], v220 offset:53248
	ds_read_b128 v[156:159], v220 offset:54272
	ds_read_b128 v[168:171], v220 offset:55296
	ds_read_b128 v[172:175], v220 offset:56320
	global_load_lds_dwordx4 v[16:17], off
	s_add_i32 m0, s38, 0x2000
	s_add_u32 s36, s36, 0x40080
	v_lshl_add_u64 v[16:17], v[162:163], 0, s[14:15]
	s_addc_u32 s37, s37, 0
	s_add_i32 s38, s43, s53
	global_load_lds_dwordx4 v[16:17], off
	v_lshl_add_u64 v[16:17], s[36:37], 0, v[188:189]
	s_mov_b32 m0, s38
	s_nop 0
	global_load_lds_dwordx4 v[16:17], off
	v_lshl_add_u64 v[16:17], s[36:37], 0, v[184:185]
	s_add_i32 m0, s38, 0x2000
	s_nop 0
	global_load_lds_dwordx4 v[16:17], off
	v_lshl_add_u64 v[16:17], v[164:165], 0, s[14:15]
	s_mov_b32 m0, s71
	s_nop 0
	global_load_lds_dwordx4 v[16:17], off
	v_lshl_add_u64 v[16:17], v[166:167], 0, s[14:15]
	s_mov_b32 m0, s72
	s_nop 0
	global_load_lds_dwordx4 v[16:17], off
	s_waitcnt vmcnt(8)
	s_waitcnt lgkmcnt(0)
	s_barrier
	s_setprio 1
	v_mfma_f32_16x16x128_f8f6f4 v[56:59], v[0:7], v[24:31], v[56:59]
	v_mfma_f32_16x16x128_f8f6f4 v[60:63], v[8:15], v[24:31], v[60:63]
	v_mfma_f32_16x16x128_f8f6f4 v[48:51], v[0:7], v[144:151], v[48:51]
	v_mfma_f32_16x16x128_f8f6f4 v[52:55], v[8:15], v[144:151], v[52:55]
	v_mfma_f32_16x16x128_f8f6f4 v[32:35], v[0:7], v[152:159], v[32:35]
	v_mfma_f32_16x16x128_f8f6f4 v[36:39], v[8:15], v[152:159], v[212:215]
	v_mfma_f32_16x16x128_f8f6f4 v[16:19], v[0:7], v[168:175], v[230:233]
	v_mfma_f32_16x16x128_f8f6f4 v[20:23], v[8:15], v[168:175], v[234:237]
	v_mfma_f32_16x16x128_f8f6f4 v[40:43], v[128:135], v[24:31], v[238:241]
	v_mfma_f32_16x16x128_f8f6f4 v[44:47], v[136:143], v[24:31], v[44:47]
	v_mfma_f32_16x16x128_f8f6f4 v[24:27], v[128:135], v[144:151], v[242:245]
	v_mfma_f32_16x16x128_f8f6f4 v[28:31], v[136:143], v[144:151], v[176:179]
	v_mfma_f32_16x16x128_f8f6f4 v[8:11], v[128:135], v[152:159], v[180:183]
	v_mfma_f32_16x16x128_f8f6f4 v[12:15], v[136:143], v[152:159], v[204:207]
	v_mfma_f32_16x16x128_f8f6f4 v[0:3], v[128:135], v[168:175], v[208:211]
	v_mfma_f32_16x16x128_f8f6f4 v[4:7], v[136:143], v[168:175], v[222:225]
	s_setprio 0
	s_barrier
	s_add_u32 s34, s34, 0x100
	s_addc_u32 s35, s35, 0
	s_add_u32 s89, s89, 0x100
	s_addc_u32 s90, s90, 0
	s_cmp_ge_u32 s3, s29
	s_mov_b32 s38, s3
	s_cbranch_scc0 .LBB0_2290
	s_and_b64 vcc, exec, s[12:13]
	s_cbranch_vccz .LBB0_2293
	s_barrier

; #define PG8_STAGE(bufoff, gbase, voff) do { _Pragma("unroll") for (int _i = 0; _i < 2; ++_i) \
;         __builtin_amdgcn_global_load_lds((const unsigned*)((const char*)(gbase) + (voff)[_i]), (LAS unsigned*)(lds + (bufoff) + ldsw + _i * 8192), 16, 0, 0); } while (0)
; #define PG8_LDA(dst, b, h) do { _Pragma("unroll") for (int m = 0; m < 4; ++m) _Pragma("unroll") for (int k = 0; k < 2; ++k) dst[m][k] = *(const LAS bf16x8*)(lds + PG8_SA(b, h) + aoff + m * 2048 + k * KOFF); } while (0)
; #define PG8_LDB(dst, b, h) do { _Pragma("unroll") for (int n = 0; n < 2; ++n) _Pragma("unroll") for (int k = 0; k < 2; ++k) dst[n][k] = *(const LAS bf16x8*)(lds + PG8_SB(b, h) + boff + n * 2048 + k * KOFF); } while (0)
; #define PG8_WAIT_V(n) asm volatile("s_waitcnt vmcnt(" #n ")" ::: "memory")
; #define PG8_WAIT_L(n) asm volatile("s_waitcnt lgkmcnt(" #n ")" ::: "memory")
; #define PG8_BAR __builtin_amdgcn_s_barrier()
; #define PG8_SCHED __builtin_amdgcn_sched_barrier(0)
; template <class Epi, bool ALIGN_EPI = true, bool FP8 = false>
; __device__ __forceinline__ void gemm_phase(LAS unsigned char* lds, const Gemm g, const StaticOrder& S, const Epi& E, const int wid) {
;     ...
;             PG8_LDB(B0, 0, 0); PG8_LDB(B1, 0, 1); PG8_SCHED; PG8_LDA(At, 0, 0); PG8_STAGE(PG8_SA(1, 1), a1 + hstep, voffA);
;             PG8_WAIT_V(8); PG8_WAIT_L(0); PG8_BAR; PG8_MMA(0, 0, At, B0); PG8_MMA(0, 1, At, B1); PG8_BAR; PG8_SCHED;
;             PG8_LDA(At, 0, 1); PG8_STAGE(PG8_SB(0, 0), b2, voffB); PG8_STAGE(PG8_SB(0, 1), b2 + hstep, voffB); PG8_STAGE(PG8_SA(0, 0), a2, voffA);
;             PG8_WAIT_V(8); PG8_WAIT_L(0); PG8_BAR; PG8_MMA(1, 0, At, B0); PG8_MMA(1, 1, At, B1); PG8_BAR; PG8_SCHED;
.LBB0_2452:
	ds_read_b128 v[152:155], v148
	ds_read_b128 v[156:159], v148 offset:1024
	ds_read_b128 v[160:163], v148 offset:2048
	ds_read_b128 v[164:167], v148 offset:3072
	ds_read_b128 v[168:171], v149
	ds_read_b128 v[172:175], v149 offset:1024
	ds_read_b128 v[176:179], v149 offset:2048
	ds_read_b128 v[180:183], v149 offset:3072
	s_add_i32 s76, s30, 2
	s_add_u32 s31, s28, 0xfff80080
	s_addc_u32 s34, s29, -1
	s_cmp_eq_u32 s43, s30
	s_cselect_b32 s30, s42, s52
	s_cselect_b32 s35, s3, s34
	s_cselect_b32 s34, s17, s31
	s_cselect_b32 s31, s19, s75
	v_lshl_add_u64 v[144:145], s[28:29], 0, v[138:139]
	s_add_i32 m0, s25, 0xc000
	ds_read_b128 v[184:187], v150
	ds_read_b128 v[188:191], v150 offset:1024
	ds_read_b128 v[192:195], v150 offset:2048
	ds_read_b128 v[196:199], v150 offset:3072
	ds_read_b128 v[200:203], v150 offset:4096
	ds_read_b128 v[204:207], v150 offset:5120
	ds_read_b128 v[208:211], v150 offset:6144
	ds_read_b128 v[212:215], v150 offset:7168
	global_load_lds_dwordx4 v[144:145], off
	v_lshl_add_u64 v[144:145], s[28:29], 0, v[140:141]
	s_add_i32 m0, s25, 0xe000
	s_nop 0
	global_load_lds_dwordx4 v[144:145], off
	s_waitcnt vmcnt(8)
	s_waitcnt lgkmcnt(0)
	s_barrier
	s_setprio 1
	v_mfma_f32_16x16x32_bf16 v[124:127], v[152:155], v[184:187], v[124:127]
	v_mfma_f32_16x16x32_bf16 v[116:119], v[160:163], v[184:187], v[116:119]
	v_mfma_f32_16x16x32_bf16 v[108:111], v[152:155], v[192:195], v[108:111]
	v_mfma_f32_16x16x32_bf16 v[100:103], v[160:163], v[192:195], v[100:103]
	v_mfma_f32_16x16x32_bf16 v[92:95], v[152:155], v[200:203], v[92:95]
	v_mfma_f32_16x16x32_bf16 v[84:87], v[160:163], v[200:203], v[84:87]
	v_mfma_f32_16x16x32_bf16 v[76:79], v[152:155], v[208:211], v[76:79]
	v_mfma_f32_16x16x32_bf16 v[68:71], v[160:163], v[208:211], v[68:71]
	v_mfma_f32_16x16x32_bf16 v[124:127], v[156:159], v[188:191], v[124:127]
	v_mfma_f32_16x16x32_bf16 v[116:119], v[164:167], v[188:191], v[116:119]
	v_mfma_f32_16x16x32_bf16 v[108:111], v[156:159], v[196:199], v[108:111]
	v_mfma_f32_16x16x32_bf16 v[100:103], v[164:167], v[196:199], v[100:103]
	v_mfma_f32_16x16x32_bf16 v[92:95], v[156:159], v[204:207], v[92:95]
	v_mfma_f32_16x16x32_bf16 v[84:87], v[164:167], v[204:207], v[84:87]
	v_mfma_f32_16x16x32_bf16 v[76:79], v[156:159], v[212:215], v[76:79]
	v_mfma_f32_16x16x32_bf16 v[68:71], v[164:167], v[212:215], v[68:71]
	v_mfma_f32_16x16x32_bf16 v[120:123], v[168:171], v[184:187], v[120:123]
	v_mfma_f32_16x16x32_bf16 v[112:115], v[176:179], v[184:187], v[112:115]
	v_mfma_f32_16x16x32_bf16 v[104:107], v[168:171], v[192:195], v[104:107]
	v_mfma_f32_16x16x32_bf16 v[96:99], v[176:179], v[192:195], v[96:99]
	v_mfma_f32_16x16x32_bf16 v[88:91], v[168:171], v[200:203], v[88:91]
	v_mfma_f32_16x16x32_bf16 v[80:83], v[176:179], v[200:203], v[80:83]
	v_mfma_f32_16x16x32_bf16 v[72:75], v[168:171], v[208:211], v[72:75]
	v_mfma_f32_16x16x32_bf16 v[64:67], v[176:179], v[208:211], v[64:67]
	v_mfma_f32_16x16x32_bf16 v[120:123], v[172:175], v[188:191], v[120:123]
	v_mfma_f32_16x16x32_bf16 v[112:115], v[180:183], v[188:191], v[112:115]
	v_mfma_f32_16x16x32_bf16 v[104:107], v[172:175], v[196:199], v[104:107]
	v_mfma_f32_16x16x32_bf16 v[96:99], v[180:183], v[196:199], v[96:99]
	v_mfma_f32_16x16x32_bf16 v[88:91], v[172:175], v[204:207], v[88:91]
	v_mfma_f32_16x16x32_bf16 v[80:83], v[180:183], v[204:207], v[80:83]
	v_mfma_f32_16x16x32_bf16 v[72:75], v[172:175], v[212:215], v[72:75]
	v_mfma_f32_16x16x32_bf16 v[64:67], v[180:183], v[212:215], v[64:67]
	s_setprio 0
	s_barrier
	s_add_i32 s77, s65, s38
	v_lshl_add_u64 v[144:145], s[30:31], 0, v[132:133]
	s_mov_b32 m0, s77
	ds_read_b128 v[184:187], v150 offset:16384
	ds_read_b128 v[188:191], v150 offset:17408
	ds_read_b128 v[192:195], v150 offset:18432
	ds_read_b128 v[196:199], v150 offset:19456
	ds_read_b128 v[200:203], v150 offset:20480
	ds_read_b128 v[204:207], v150 offset:21504
	ds_read_b128 v[208:211], v150 offset:22528
	ds_read_b128 v[212:215], v150 offset:23552
	global_load_lds_dwordx4 v[144:145], off
	s_add_i32 m0, s77, 0x2000
	s_add_u32 s78, s30, 0x80000
	v_lshl_add_u64 v[216:217], s[30:31], 0, v[128:129]
	s_addc_u32 s79, s31, 0
	s_add_i32 s77, s66, s38
	global_load_lds_dwordx4 v[216:217], off
	v_lshl_add_u64 v[218:219], s[78:79], 0, v[132:133]
	s_mov_b32 m0, s77
	v_lshl_add_u64 v[220:221], s[34:35], 0, v[130:131]
	global_load_lds_dwordx4 v[218:219], off
	v_lshl_add_u64 v[218:219], s[78:79], 0, v[128:129]
	s_add_i32 m0, s77, 0x2000
	s_nop 0
	global_load_lds_dwordx4 v[218:219], off
	v_lshl_add_u64 v[218:219], s[34:35], 0, v[134:135]
	s_mov_b32 m0, s25
	s_nop 0
	global_load_lds_dwordx4 v[218:219], off
	s_mov_b32 m0, s27
	s_nop 0
	global_load_lds_dwordx4 v[220:221], off
	s_waitcnt vmcnt(8)
	s_waitcnt lgkmcnt(0)
	s_barrier
; #define PG8_STAGE(bufoff, gbase, voff) do { _Pragma("unroll") for (int _i = 0; _i < 2; ++_i) \
;         __builtin_amdgcn_global_load_lds((const unsigned*)((const char*)(gbase) + (voff)[_i]), (LAS unsigned*)(lds + (bufoff) + ldsw + _i * 8192), 16, 0, 0); } while (0)
; #define PG8_LDA(dst, b, h) do { _Pragma("unroll") for (int m = 0; m < 4; ++m) _Pragma("unroll") for (int k = 0; k < 2; ++k) dst[m][k] = *(const LAS bf16x8*)(lds + PG8_SA(b, h) + aoff + m * 2048 + k * KOFF); } while (0)
; #define PG8_LDB(dst, b, h) do { _Pragma("unroll") for (int n = 0; n < 2; ++n) _Pragma("unroll") for (int k = 0; k < 2; ++k) dst[n][k] = *(const LAS bf16x8*)(lds + PG8_SB(b, h) + boff + n * 2048 + k * KOFF); } while (0)
; #define PG8_WAIT_V(n) asm volatile("s_waitcnt vmcnt(" #n ")" ::: "memory")
; #define PG8_WAIT_L(n) asm volatile("s_waitcnt lgkmcnt(" #n ")" ::: "memory")
; #define PG8_BAR __builtin_amdgcn_s_barrier()
; #define PG8_SCHED __builtin_amdgcn_sched_barrier(0)
; template <class Epi, bool ALIGN_EPI = true, bool FP8 = false>
; __device__ __forceinline__ void gemm_phase(LAS unsigned char* lds, const Gemm g, const StaticOrder& S, const Epi& E, const int wid) {
;     ...
;             PG8_WAIT_V(8); PG8_WAIT_L(0); PG8_BAR; PG8_MMA(1, 0, At, B0); PG8_MMA(1, 1, At, B1); PG8_BAR; PG8_SCHED;
;             PG8_LDB(B0, 1, 0); PG8_LDB(B1, 1, 1); PG8_SCHED; PG8_LDA(At, 1, 0); PG8_STAGE(PG8_SA(0, 1), a2 + hstep, voffA);
;             PG8_WAIT_V(8); PG8_WAIT_L(0); PG8_BAR; PG8_MMA(0, 0, At, B0); PG8_MMA(0, 1, At, B1); PG8_BAR; PG8_SCHED;
	s_setprio 1
	v_mfma_f32_16x16x32_bf16 v[60:63], v[152:155], v[184:187], v[60:63]
	v_mfma_f32_16x16x32_bf16 v[52:55], v[160:163], v[184:187], v[52:55]
	v_mfma_f32_16x16x32_bf16 v[44:47], v[152:155], v[192:195], v[44:47]
	v_mfma_f32_16x16x32_bf16 v[36:39], v[160:163], v[192:195], v[36:39]
	v_mfma_f32_16x16x32_bf16 v[28:31], v[152:155], v[200:203], v[28:31]
	v_mfma_f32_16x16x32_bf16 v[20:23], v[160:163], v[200:203], v[20:23]
	v_mfma_f32_16x16x32_bf16 v[12:15], v[152:155], v[208:211], v[12:15]
	v_mfma_f32_16x16x32_bf16 v[4:7], v[160:163], v[208:211], v[4:7]
	v_mfma_f32_16x16x32_bf16 v[60:63], v[156:159], v[188:191], v[60:63]
	v_mfma_f32_16x16x32_bf16 v[52:55], v[164:167], v[188:191], v[52:55]
	v_mfma_f32_16x16x32_bf16 v[44:47], v[156:159], v[196:199], v[44:47]
	v_mfma_f32_16x16x32_bf16 v[36:39], v[164:167], v[196:199], v[36:39]
	v_mfma_f32_16x16x32_bf16 v[28:31], v[156:159], v[204:207], v[28:31]
	v_mfma_f32_16x16x32_bf16 v[20:23], v[164:167], v[204:207], v[20:23]
	v_mfma_f32_16x16x32_bf16 v[12:15], v[156:159], v[212:215], v[12:15]
	v_mfma_f32_16x16x32_bf16 v[4:7], v[164:167], v[212:215], v[4:7]
	v_mfma_f32_16x16x32_bf16 v[56:59], v[168:171], v[184:187], v[56:59]
	v_mfma_f32_16x16x32_bf16 v[48:51], v[176:179], v[184:187], v[48:51]
	v_mfma_f32_16x16x32_bf16 v[40:43], v[168:171], v[192:195], v[40:43]
	v_mfma_f32_16x16x32_bf16 v[32:35], v[176:179], v[192:195], v[32:35]
	v_mfma_f32_16x16x32_bf16 v[24:27], v[168:171], v[200:203], v[24:27]
	v_mfma_f32_16x16x32_bf16 v[16:19], v[176:179], v[200:203], v[16:19]
	v_mfma_f32_16x16x32_bf16 v[8:11], v[168:171], v[208:211], v[8:11]
	v_mfma_f32_16x16x32_bf16 v[0:3], v[176:179], v[208:211], v[0:3]
	v_mfma_f32_16x16x32_bf16 v[56:59], v[172:175], v[188:191], v[56:59]
	v_mfma_f32_16x16x32_bf16 v[48:51], v[180:183], v[188:191], v[48:51]
	v_mfma_f32_16x16x32_bf16 v[40:43], v[172:175], v[196:199], v[40:43]
	v_mfma_f32_16x16x32_bf16 v[32:35], v[180:183], v[196:199], v[32:35]
	v_mfma_f32_16x16x32_bf16 v[24:27], v[172:175], v[204:207], v[24:27]
	v_mfma_f32_16x16x32_bf16 v[16:19], v[180:183], v[204:207], v[16:19]
	v_mfma_f32_16x16x32_bf16 v[8:11], v[172:175], v[212:215], v[8:11]
	v_mfma_f32_16x16x32_bf16 v[0:3], v[180:183], v[212:215], v[0:3]
	s_setprio 0
	s_barrier
	s_add_i32 s77, 0, 0x18000
	s_add_i32 s78, 0, 0x1c000
	v_add_u32_e32 v164, s77, v147
	v_add_u32_e32 v180, s78, v147
	ds_read_b128 v[152:155], v164
	ds_read_b128 v[156:159], v164 offset:1024
	ds_read_b128 v[160:163], v164 offset:2048
	ds_read_b128 v[164:167], v164 offset:3072
	ds_read_b128 v[168:171], v180
	ds_read_b128 v[172:175], v180 offset:1024
	ds_read_b128 v[176:179], v180 offset:2048
	ds_read_b128 v[180:183], v180 offset:3072
	s_add_u32 s34, s34, 0x80000
	s_addc_u32 s35, s35, 0
	s_mov_b32 m0, s39
	v_lshl_add_u64 v[222:223], s[34:35], 0, v[134:135]
	ds_read_b128 v[184:187], v150 offset:32768
	ds_read_b128 v[188:191], v150 offset:33792
	ds_read_b128 v[192:195], v150 offset:34816
	ds_read_b128 v[196:199], v150 offset:35840
	ds_read_b128 v[200:203], v150 offset:36864
	ds_read_b128 v[204:207], v150 offset:37888
	ds_read_b128 v[208:211], v150 offset:38912
	ds_read_b128 v[212:215], v150 offset:39936
	global_load_lds_dwordx4 v[222:223], off
	v_lshl_add_u64 v[222:223], s[34:35], 0, v[130:131]
	s_mov_b32 m0, s48
	s_nop 0
	global_load_lds_dwordx4 v[222:223], off
	s_waitcnt vmcnt(8)
	s_waitcnt lgkmcnt(0)
	s_barrier
	s_setprio 1
	v_mfma_f32_16x16x32_bf16 v[124:127], v[152:155], v[184:187], v[124:127]
	v_mfma_f32_16x16x32_bf16 v[116:119], v[160:163], v[184:187], v[116:119]
	v_mfma_f32_16x16x32_bf16 v[108:111], v[152:155], v[192:195], v[108:111]
	v_mfma_f32_16x16x32_bf16 v[100:103], v[160:163], v[192:195], v[100:103]
	v_mfma_f32_16x16x32_bf16 v[92:95], v[152:155], v[200:203], v[92:95]
	v_mfma_f32_16x16x32_bf16 v[84:87], v[160:163], v[200:203], v[84:87]
	v_mfma_f32_16x16x32_bf16 v[76:79], v[152:155], v[208:211], v[76:79]
	v_mfma_f32_16x16x32_bf16 v[68:71], v[160:163], v[208:211], v[68:71]
	v_mfma_f32_16x16x32_bf16 v[124:127], v[156:159], v[188:191], v[124:127]
	v_mfma_f32_16x16x32_bf16 v[116:119], v[164:167], v[188:191], v[116:119]
	v_mfma_f32_16x16x32_bf16 v[108:111], v[156:159], v[196:199], v[108:111]
	v_mfma_f32_16x16x32_bf16 v[100:103], v[164:167], v[196:199], v[100:103]
	v_mfma_f32_16x16x32_bf16 v[92:95], v[156:159], v[204:207], v[92:95]
	v_mfma_f32_16x16x32_bf16 v[84:87], v[164:167], v[204:207], v[84:87]
	v_mfma_f32_16x16x32_bf16 v[76:79], v[156:159], v[212:215], v[76:79]
	v_mfma_f32_16x16x32_bf16 v[68:71], v[164:167], v[212:215], v[68:71]
	v_mfma_f32_16x16x32_bf16 v[120:123], v[168:171], v[184:187], v[120:123]
	v_mfma_f32_16x16x32_bf16 v[112:115], v[176:179], v[184:187], v[112:115]
	v_mfma_f32_16x16x32_bf16 v[104:107], v[168:171], v[192:195], v[104:107]
	v_mfma_f32_16x16x32_bf16 v[96:99], v[176:179], v[192:195], v[96:99]
	v_mfma_f32_16x16x32_bf16 v[88:91], v[168:171], v[200:203], v[88:91]
	v_mfma_f32_16x16x32_bf16 v[80:83], v[176:179], v[200:203], v[80:83]
	v_mfma_f32_16x16x32_bf16 v[72:75], v[168:171], v[208:211], v[72:75]
	v_mfma_f32_16x16x32_bf16 v[64:67], v[176:179], v[208:211], v[64:67]
	v_mfma_f32_16x16x32_bf16 v[120:123], v[172:175], v[188:191], v[120:123]
	v_mfma_f32_16x16x32_bf16 v[112:115], v[180:183], v[188:191], v[112:115]
	v_mfma_f32_16x16x32_bf16 v[104:107], v[172:175], v[196:199], v[104:107]
	v_mfma_f32_16x16x32_bf16 v[96:99], v[180:183], v[196:199], v[96:99]
	v_mfma_f32_16x16x32_bf16 v[88:91], v[172:175], v[204:207], v[88:91]
	v_mfma_f32_16x16x32_bf16 v[80:83], v[180:183], v[204:207], v[80:83]
	v_mfma_f32_16x16x32_bf16 v[72:75], v[172:175], v[212:215], v[72:75]
	v_mfma_f32_16x16x32_bf16 v[64:67], v[180:183], v[212:215], v[64:67]
	s_setprio 0
	s_barrier
; #define PG8_STAGE(bufoff, gbase, voff) do { _Pragma("unroll") for (int _i = 0; _i < 2; ++_i) \
;         __builtin_amdgcn_global_load_lds((const unsigned*)((const char*)(gbase) + (voff)[_i]), (LAS unsigned*)(lds + (bufoff) + ldsw + _i * 8192), 16, 0, 0); } while (0)
; #define PG8_LDA(dst, b, h) do { _Pragma("unroll") for (int m = 0; m < 4; ++m) _Pragma("unroll") for (int k = 0; k < 2; ++k) dst[m][k] = *(const LAS bf16x8*)(lds + PG8_SA(b, h) + aoff + m * 2048 + k * KOFF); } while (0)
; #define PG8_WAIT_V(n) asm volatile("s_waitcnt vmcnt(" #n ")" ::: "memory")
; #define PG8_WAIT_L(n) asm volatile("s_waitcnt lgkmcnt(" #n ")" ::: "memory")
; #define PG8_BAR __builtin_amdgcn_s_barrier()
; #define PG8_SCHED __builtin_amdgcn_sched_barrier(0)
; template <class Epi, bool ALIGN_EPI = true, bool FP8 = false>
; __device__ __forceinline__ void gemm_phase(LAS unsigned char* lds, const Gemm g, const StaticOrder& S, const Epi& E, const int wid) {
;     ...
;             PG8_LDA(At, 1, 1); PG8_STAGE(PG8_SB(1, 0), b3, voffB); PG8_STAGE(PG8_SB(1, 1), b3 + hstep, voffB); PG8_STAGE(PG8_SA(1, 0), a3, voffA);
;             PG8_WAIT_V(8); PG8_WAIT_L(0); PG8_BAR; PG8_MMA(1, 0, At, B0); PG8_MMA(1, 1, At, B1); PG8_BAR; PG8_SCHED;
;         }
	s_add_i32 s34, s77, s38
	v_lshl_add_u64 v[144:145], v[144:145], 0, s[14:15]
	s_mov_b32 m0, s34
	ds_read_b128 v[184:187], v150 offset:49152
	ds_read_b128 v[188:191], v150 offset:50176
	ds_read_b128 v[192:195], v150 offset:51200
	ds_read_b128 v[196:199], v150 offset:52224
	ds_read_b128 v[200:203], v150 offset:53248
	ds_read_b128 v[204:207], v150 offset:54272
	ds_read_b128 v[208:211], v150 offset:55296
	ds_read_b128 v[212:215], v150 offset:56320
	global_load_lds_dwordx4 v[144:145], off
	s_add_i32 m0, s34, 0x2000
	s_add_u32 s30, s30, 0x80080
	v_lshl_add_u64 v[144:145], v[216:217], 0, s[14:15]
	s_addc_u32 s31, s31, 0
	s_add_i32 s34, s78, s38
	global_load_lds_dwordx4 v[144:145], off
	v_lshl_add_u64 v[144:145], s[30:31], 0, v[132:133]
	s_mov_b32 m0, s34
	s_nop 0
	global_load_lds_dwordx4 v[144:145], off
	v_lshl_add_u64 v[144:145], s[30:31], 0, v[128:129]
	s_add_i32 m0, s34, 0x2000
	s_nop 0
	global_load_lds_dwordx4 v[144:145], off
	v_lshl_add_u64 v[144:145], v[218:219], 0, s[14:15]
	s_mov_b32 m0, s53
	s_nop 0
	global_load_lds_dwordx4 v[144:145], off
	v_lshl_add_u64 v[144:145], v[220:221], 0, s[14:15]
	s_mov_b32 m0, s55
	s_nop 0
	global_load_lds_dwordx4 v[144:145], off
	s_waitcnt vmcnt(8)
	s_waitcnt lgkmcnt(0)
	s_barrier
	s_setprio 1
	v_mfma_f32_16x16x32_bf16 v[60:63], v[152:155], v[184:187], v[60:63]
	v_mfma_f32_16x16x32_bf16 v[52:55], v[160:163], v[184:187], v[52:55]
	v_mfma_f32_16x16x32_bf16 v[44:47], v[152:155], v[192:195], v[44:47]
	v_mfma_f32_16x16x32_bf16 v[36:39], v[160:163], v[192:195], v[36:39]
	v_mfma_f32_16x16x32_bf16 v[28:31], v[152:155], v[200:203], v[28:31]
	v_mfma_f32_16x16x32_bf16 v[20:23], v[160:163], v[200:203], v[20:23]
	v_mfma_f32_16x16x32_bf16 v[12:15], v[152:155], v[208:211], v[12:15]
	v_mfma_f32_16x16x32_bf16 v[4:7], v[160:163], v[208:211], v[4:7]
	v_mfma_f32_16x16x32_bf16 v[60:63], v[156:159], v[188:191], v[60:63]
	v_mfma_f32_16x16x32_bf16 v[52:55], v[164:167], v[188:191], v[52:55]
	v_mfma_f32_16x16x32_bf16 v[44:47], v[156:159], v[196:199], v[44:47]
	v_mfma_f32_16x16x32_bf16 v[36:39], v[164:167], v[196:199], v[36:39]
	v_mfma_f32_16x16x32_bf16 v[28:31], v[156:159], v[204:207], v[28:31]
	v_mfma_f32_16x16x32_bf16 v[20:23], v[164:167], v[204:207], v[20:23]
	v_mfma_f32_16x16x32_bf16 v[12:15], v[156:159], v[212:215], v[12:15]
	v_mfma_f32_16x16x32_bf16 v[4:7], v[164:167], v[212:215], v[4:7]
	v_mfma_f32_16x16x32_bf16 v[56:59], v[168:171], v[184:187], v[56:59]
	v_mfma_f32_16x16x32_bf16 v[48:51], v[176:179], v[184:187], v[48:51]
	v_mfma_f32_16x16x32_bf16 v[40:43], v[168:171], v[192:195], v[40:43]
	v_mfma_f32_16x16x32_bf16 v[32:35], v[176:179], v[192:195], v[32:35]
	v_mfma_f32_16x16x32_bf16 v[24:27], v[168:171], v[200:203], v[24:27]
	v_mfma_f32_16x16x32_bf16 v[16:19], v[176:179], v[200:203], v[16:19]
	v_mfma_f32_16x16x32_bf16 v[8:11], v[168:171], v[208:211], v[8:11]
	v_mfma_f32_16x16x32_bf16 v[0:3], v[176:179], v[208:211], v[0:3]
	v_mfma_f32_16x16x32_bf16 v[56:59], v[172:175], v[188:191], v[56:59]
	v_mfma_f32_16x16x32_bf16 v[48:51], v[180:183], v[188:191], v[48:51]
	v_mfma_f32_16x16x32_bf16 v[40:43], v[172:175], v[196:199], v[40:43]
	v_mfma_f32_16x16x32_bf16 v[32:35], v[180:183], v[196:199], v[32:35]
	v_mfma_f32_16x16x32_bf16 v[24:27], v[172:175], v[204:207], v[24:27]
	v_mfma_f32_16x16x32_bf16 v[16:19], v[180:183], v[204:207], v[16:19]
	v_mfma_f32_16x16x32_bf16 v[8:11], v[172:175], v[212:215], v[8:11]
	v_mfma_f32_16x16x32_bf16 v[0:3], v[180:183], v[212:215], v[0:3]
	s_setprio 0
	s_barrier
	s_add_u32 s28, s28, 0x100
	s_addc_u32 s29, s29, 0
	s_add_u32 s52, s52, 0x100
	s_addc_u32 s75, s75, 0
	s_cmp_ge_u32 s76, s54
	s_mov_b32 s30, s76
	s_cbranch_scc0 .LBB0_2452
	s_and_b64 vcc, exec, s[12:13]
	s_cbranch_vccz .LBB0_2455

; #define PG8_STAGE(bufoff, gbase, voff) do { _Pragma("unroll") for (int _i = 0; _i < 2; ++_i) \
;         __builtin_amdgcn_global_load_lds((const unsigned*)((const char*)(gbase) + (voff)[_i]), (LAS unsigned*)(lds + (bufoff) + ldsw + _i * 8192), 16, 0, 0); } while (0)
; #define PG8_LDA(dst, b, h) do { _Pragma("unroll") for (int m = 0; m < 4; ++m) _Pragma("unroll") for (int k = 0; k < 2; ++k) dst[m][k] = *(const LAS bf16x8*)(lds + PG8_SA(b, h) + aoff + m * 2048 + k * KOFF); } while (0)
; #define PG8_LDB(dst, b, h) do { _Pragma("unroll") for (int n = 0; n < 2; ++n) _Pragma("unroll") for (int k = 0; k < 2; ++k) dst[n][k] = *(const LAS bf16x8*)(lds + PG8_SB(b, h) + boff + n * 2048 + k * KOFF); } while (0)
; #define PG8_WAIT_V(n) asm volatile("s_waitcnt vmcnt(" #n ")" ::: "memory")
; #define PG8_WAIT_L(n) asm volatile("s_waitcnt lgkmcnt(" #n ")" ::: "memory")
; #define PG8_BAR __builtin_amdgcn_s_barrier()
; #define PG8_SCHED __builtin_amdgcn_sched_barrier(0)
; template <class Epi, bool ALIGN_EPI = true, bool FP8 = false>
; __device__ __forceinline__ void gemm_phase(LAS unsigned char* lds, const Gemm g, const StaticOrder& S, const Epi& E, const int wid) {
;     ...
;             PG8_LDB(B0, 0, 0); PG8_LDB(B1, 0, 1); PG8_SCHED; PG8_LDA(At, 0, 0); PG8_STAGE(PG8_SA(1, 1), a1 + hstep, voffA);
;             PG8_WAIT_V(8); PG8_WAIT_L(0); PG8_BAR; PG8_MMA(0, 0, At, B0); PG8_MMA(0, 1, At, B1); PG8_BAR; PG8_SCHED;
;             PG8_LDA(At, 0, 1); PG8_STAGE(PG8_SB(0, 0), b2, voffB); PG8_STAGE(PG8_SB(0, 1), b2 + hstep, voffB); PG8_STAGE(PG8_SA(0, 0), a2, voffA);
;             PG8_WAIT_V(8); PG8_WAIT_L(0); PG8_BAR; PG8_MMA(1, 0, At, B0); PG8_MMA(1, 1, At, B1); PG8_BAR; PG8_SCHED;
.LBB0_2536:
	ds_read_b128 v[152:155], v188
	ds_read_b128 v[156:159], v188 offset:1024
	ds_read_b128 v[144:147], v188 offset:2048
	ds_read_b128 v[148:151], v188 offset:3072
	ds_read_b128 v[136:139], v189
	ds_read_b128 v[140:143], v189 offset:1024
	ds_read_b128 v[128:131], v189 offset:2048
	ds_read_b128 v[132:135], v189 offset:3072
	s_add_i32 s42, s26, 2
	s_add_u32 s27, s24, 0xfff50080
	s_addc_u32 s28, s25, -1
	s_cmp_eq_u32 s81, s26
	s_cselect_b32 s26, s20, s82
	s_cselect_b32 s29, s7, s28
	s_cselect_b32 s28, s6, s27
	s_cselect_b32 s27, s21, s83
	v_lshl_add_u64 v[216:217], s[24:25], 0, v[172:173]
	s_add_i32 m0, s34, 0xc000
	ds_read_b128 v[178:181], v190
	ds_read_b128 v[182:185], v190 offset:1024
	ds_read_b128 v[192:195], v190 offset:2048
	ds_read_b128 v[196:199], v190 offset:3072
	ds_read_b128 v[200:203], v190 offset:4096
	ds_read_b128 v[204:207], v190 offset:5120
	ds_read_b128 v[208:211], v190 offset:6144
	ds_read_b128 v[212:215], v190 offset:7168
	global_load_lds_dwordx4 v[216:217], off
	v_lshl_add_u64 v[216:217], s[24:25], 0, v[174:175]
	s_add_i32 m0, s34, 0xe000
	s_nop 0
	global_load_lds_dwordx4 v[216:217], off
	s_waitcnt vmcnt(8)
	s_waitcnt lgkmcnt(0)
	s_barrier
	s_setprio 1
	v_mfma_f32_16x16x128_f8f6f4 v[120:123], v[152:159], v[178:185], v[120:123]
	v_mfma_f32_16x16x128_f8f6f4 v[124:127], v[144:151], v[178:185], v[124:127]
	v_mfma_f32_16x16x128_f8f6f4 v[112:115], v[152:159], v[192:199], v[112:115]
	v_mfma_f32_16x16x128_f8f6f4 v[116:119], v[144:151], v[192:199], v[116:119]
	v_mfma_f32_16x16x128_f8f6f4 v[96:99], v[152:159], v[200:207], v[96:99]
	v_mfma_f32_16x16x128_f8f6f4 v[100:103], v[144:151], v[200:207], v[100:103]
	v_mfma_f32_16x16x128_f8f6f4 v[80:83], v[152:159], v[208:215], v[80:83]
	v_mfma_f32_16x16x128_f8f6f4 v[84:87], v[144:151], v[208:215], v[84:87]
	v_mfma_f32_16x16x128_f8f6f4 v[104:107], v[136:143], v[178:185], v[104:107]
	v_mfma_f32_16x16x128_f8f6f4 v[108:111], v[128:135], v[178:185], v[108:111]
	v_mfma_f32_16x16x128_f8f6f4 v[88:91], v[136:143], v[192:199], v[88:91]
	v_mfma_f32_16x16x128_f8f6f4 v[92:95], v[128:135], v[192:199], v[92:95]
	v_mfma_f32_16x16x128_f8f6f4 v[72:75], v[136:143], v[200:207], v[72:75]
	v_mfma_f32_16x16x128_f8f6f4 v[76:79], v[128:135], v[200:207], v[76:79]
	v_mfma_f32_16x16x128_f8f6f4 v[64:67], v[136:143], v[208:215], v[64:67]
	v_mfma_f32_16x16x128_f8f6f4 v[68:71], v[128:135], v[208:215], v[68:71]
	s_setprio 0
	s_barrier
	s_add_i32 s43, s64, s31
	v_lshl_add_u64 v[178:179], s[26:27], 0, v[162:163]
	s_mov_b32 m0, s43
	ds_read_b128 v[192:195], v190 offset:16384
	ds_read_b128 v[196:199], v190 offset:17408
	ds_read_b128 v[200:203], v190 offset:18432
	ds_read_b128 v[204:207], v190 offset:19456
	ds_read_b128 v[208:211], v190 offset:20480
	ds_read_b128 v[212:215], v190 offset:21504
	ds_read_b128 v[216:219], v190 offset:22528
	ds_read_b128 v[220:223], v190 offset:23552
	global_load_lds_dwordx4 v[178:179], off
	s_add_i32 m0, s43, 0x2000
	s_add_u32 s84, s26, 0xb0000
	v_lshl_add_u64 v[180:181], s[26:27], 0, v[166:167]
	s_addc_u32 s85, s27, 0
	s_add_i32 s43, s65, s31
	global_load_lds_dwordx4 v[180:181], off
	v_lshl_add_u64 v[182:183], s[84:85], 0, v[162:163]
	s_mov_b32 m0, s43
	v_lshl_add_u64 v[184:185], s[28:29], 0, v[164:165]
	global_load_lds_dwordx4 v[182:183], off
	v_lshl_add_u64 v[182:183], s[84:85], 0, v[166:167]
	s_add_i32 m0, s43, 0x2000
	s_nop 0
	global_load_lds_dwordx4 v[182:183], off
	v_lshl_add_u64 v[182:183], s[28:29], 0, v[160:161]
	s_mov_b32 m0, s34
	s_nop 0
	global_load_lds_dwordx4 v[182:183], off
	s_mov_b32 m0, s35
	s_nop 0
	global_load_lds_dwordx4 v[184:185], off
	s_waitcnt vmcnt(8)
	s_waitcnt lgkmcnt(0)
	s_barrier
	s_setprio 1
	v_mfma_f32_16x16x128_f8f6f4 v[56:59], v[152:159], v[192:199], v[56:59]
	v_mfma_f32_16x16x128_f8f6f4 v[60:63], v[144:151], v[192:199], v[60:63]
	v_mfma_f32_16x16x128_f8f6f4 v[48:51], v[152:159], v[200:207], v[48:51]
	v_mfma_f32_16x16x128_f8f6f4 v[52:55], v[144:151], v[200:207], v[52:55]
	v_mfma_f32_16x16x128_f8f6f4 v[32:35], v[152:159], v[208:215], v[32:35]
	v_mfma_f32_16x16x128_f8f6f4 v[224:227], v[144:151], v[208:215], v[36:39]
	v_mfma_f32_16x16x128_f8f6f4 v[228:231], v[152:159], v[216:223], v[16:19]
	v_mfma_f32_16x16x128_f8f6f4 v[232:235], v[144:151], v[216:223], v[20:23]
	v_mfma_f32_16x16x128_f8f6f4 v[44:47], v[128:135], v[192:199], v[44:47]
	v_mfma_f32_16x16x128_f8f6f4 v[236:239], v[136:143], v[192:199], v[40:43]
	v_mfma_f32_16x16x128_f8f6f4 v[240:243], v[136:143], v[200:207], v[24:27]
	v_mfma_f32_16x16x128_f8f6f4 v[200:203], v[128:135], v[200:207], v[28:31]
	v_mfma_f32_16x16x128_f8f6f4 v[204:207], v[136:143], v[208:215], v[8:11]
	v_mfma_f32_16x16x128_f8f6f4 v[208:211], v[128:135], v[208:215], v[12:15]
	v_mfma_f32_16x16x128_f8f6f4 v[212:215], v[136:143], v[216:223], v[0:3]
	v_mfma_f32_16x16x128_f8f6f4 v[216:219], v[128:135], v[216:223], v[4:7]
	s_setprio 0
	s_barrier
; #define PG8_STAGE(bufoff, gbase, voff) do { _Pragma("unroll") for (int _i = 0; _i < 2; ++_i) \
;         __builtin_amdgcn_global_load_lds((const unsigned*)((const char*)(gbase) + (voff)[_i]), (LAS unsigned*)(lds + (bufoff) + ldsw + _i * 8192), 16, 0, 0); } while (0)
; #define PG8_LDA(dst, b, h) do { _Pragma("unroll") for (int m = 0; m < 4; ++m) _Pragma("unroll") for (int k = 0; k < 2; ++k) dst[m][k] = *(const LAS bf16x8*)(lds + PG8_SA(b, h) + aoff + m * 2048 + k * KOFF); } while (0)
; #define PG8_LDB(dst, b, h) do { _Pragma("unroll") for (int n = 0; n < 2; ++n) _Pragma("unroll") for (int k = 0; k < 2; ++k) dst[n][k] = *(const LAS bf16x8*)(lds + PG8_SB(b, h) + boff + n * 2048 + k * KOFF); } while (0)
; #define PG8_WAIT_V(n) asm volatile("s_waitcnt vmcnt(" #n ")" ::: "memory")
; #define PG8_WAIT_L(n) asm volatile("s_waitcnt lgkmcnt(" #n ")" ::: "memory")
; #define PG8_BAR __builtin_amdgcn_s_barrier()
; #define PG8_SCHED __builtin_amdgcn_sched_barrier(0)
; template <class Epi, bool ALIGN_EPI = true, bool FP8 = false>
; __device__ __forceinline__ void gemm_phase(LAS unsigned char* lds, const Gemm g, const StaticOrder& S, const Epi& E, const int wid) {
;     ...
;             PG8_LDB(B0, 1, 0); PG8_LDB(B1, 1, 1); PG8_SCHED; PG8_LDA(At, 1, 0); PG8_STAGE(PG8_SA(0, 1), a2 + hstep, voffA);
;             PG8_WAIT_V(8); PG8_WAIT_L(0); PG8_BAR; PG8_MMA(0, 0, At, B0); PG8_MMA(0, 1, At, B1); PG8_BAR; PG8_SCHED;
;             PG8_LDA(At, 1, 1); PG8_STAGE(PG8_SB(1, 0), b3, voffB); PG8_STAGE(PG8_SB(1, 1), b3 + hstep, voffB); PG8_STAGE(PG8_SA(1, 0), a3, voffA);
;             PG8_WAIT_V(8); PG8_WAIT_L(0); PG8_BAR; PG8_MMA(1, 0, At, B0); PG8_MMA(1, 1, At, B1); PG8_BAR; PG8_SCHED;
;         }
;         if constexpr (ALIGN_EPI) { if (wr == 0) PG8_BAR; }
	s_add_i32 s43, 0, 0x18000
	s_add_i32 s54, 0, 0x1c000
	s_nop 0
	v_add_u32_e32 v12, s43, v187
	v_add_u32_e32 v16, s54, v187
	ds_read_b128 v[0:3], v12
	ds_read_b128 v[4:7], v12 offset:1024
	ds_read_b128 v[8:11], v12 offset:2048
	ds_read_b128 v[12:15], v12 offset:3072
	ds_read_b128 v[128:131], v16
	ds_read_b128 v[132:135], v16 offset:1024
	ds_read_b128 v[136:139], v16 offset:2048
	ds_read_b128 v[140:143], v16 offset:3072
	s_add_u32 s28, s28, 0xb0000
	s_addc_u32 s29, s29, 0
	s_mov_b32 m0, s36
	v_lshl_add_u64 v[152:153], s[28:29], 0, v[160:161]
	ds_read_b128 v[16:19], v190 offset:32768
	ds_read_b128 v[20:23], v190 offset:33792
	ds_read_b128 v[24:27], v190 offset:34816
	ds_read_b128 v[28:31], v190 offset:35840
	ds_read_b128 v[36:39], v190 offset:36864
	ds_read_b128 v[40:43], v190 offset:37888
	ds_read_b128 v[144:147], v190 offset:38912
	ds_read_b128 v[148:151], v190 offset:39936
	global_load_lds_dwordx4 v[152:153], off
	v_lshl_add_u64 v[152:153], s[28:29], 0, v[164:165]
	s_mov_b32 m0, s37
	s_nop 0
	global_load_lds_dwordx4 v[152:153], off
	s_waitcnt vmcnt(8)
	s_waitcnt lgkmcnt(0)
	s_barrier
	s_setprio 1
	v_mfma_f32_16x16x128_f8f6f4 v[120:123], v[0:7], v[16:23], v[120:123]
	v_mfma_f32_16x16x128_f8f6f4 v[124:127], v[8:15], v[16:23], v[124:127]
	v_mfma_f32_16x16x128_f8f6f4 v[112:115], v[0:7], v[24:31], v[112:115]
	v_mfma_f32_16x16x128_f8f6f4 v[116:119], v[8:15], v[24:31], v[116:119]
	v_mfma_f32_16x16x128_f8f6f4 v[96:99], v[0:7], v[36:43], v[96:99]
	v_mfma_f32_16x16x128_f8f6f4 v[100:103], v[8:15], v[36:43], v[100:103]
	v_mfma_f32_16x16x128_f8f6f4 v[80:83], v[0:7], v[144:151], v[80:83]
	v_mfma_f32_16x16x128_f8f6f4 v[84:87], v[8:15], v[144:151], v[84:87]
	v_mfma_f32_16x16x128_f8f6f4 v[104:107], v[128:135], v[16:23], v[104:107]
	v_mfma_f32_16x16x128_f8f6f4 v[108:111], v[136:143], v[16:23], v[108:111]
	v_mfma_f32_16x16x128_f8f6f4 v[88:91], v[128:135], v[24:31], v[88:91]
	v_mfma_f32_16x16x128_f8f6f4 v[92:95], v[136:143], v[24:31], v[92:95]
	v_mfma_f32_16x16x128_f8f6f4 v[72:75], v[128:135], v[36:43], v[72:75]
	v_mfma_f32_16x16x128_f8f6f4 v[76:79], v[136:143], v[36:43], v[76:79]
	v_mfma_f32_16x16x128_f8f6f4 v[64:67], v[128:135], v[144:151], v[64:67]
	v_mfma_f32_16x16x128_f8f6f4 v[68:71], v[136:143], v[144:151], v[68:71]
	s_setprio 0
	s_barrier
	s_add_i32 s28, s43, s31
	v_lshl_add_u64 v[16:17], v[178:179], 0, s[14:15]
	s_mov_b32 m0, s28
	ds_read_b128 v[24:27], v190 offset:49152
	ds_read_b128 v[28:31], v190 offset:50176
	ds_read_b128 v[144:147], v190 offset:51200
	ds_read_b128 v[148:151], v190 offset:52224
	ds_read_b128 v[152:155], v190 offset:53248
	ds_read_b128 v[156:159], v190 offset:54272
	ds_read_b128 v[192:195], v190 offset:55296
	ds_read_b128 v[196:199], v190 offset:56320
	global_load_lds_dwordx4 v[16:17], off
	s_add_i32 m0, s28, 0x2000
	s_add_u32 s26, s26, 0xb0080
	v_lshl_add_u64 v[16:17], v[180:181], 0, s[14:15]
	s_addc_u32 s27, s27, 0
	s_add_i32 s28, s54, s31
	global_load_lds_dwordx4 v[16:17], off
	v_lshl_add_u64 v[16:17], s[26:27], 0, v[162:163]
	s_mov_b32 m0, s28
	s_nop 0
	global_load_lds_dwordx4 v[16:17], off
	v_lshl_add_u64 v[16:17], s[26:27], 0, v[166:167]
	s_add_i32 m0, s28, 0x2000
	s_nop 0
	global_load_lds_dwordx4 v[16:17], off
	v_lshl_add_u64 v[16:17], v[182:183], 0, s[14:15]
	s_mov_b32 m0, s52
	s_nop 0
	global_load_lds_dwordx4 v[16:17], off
	v_lshl_add_u64 v[16:17], v[184:185], 0, s[14:15]
	s_mov_b32 m0, s53
	s_nop 0
	global_load_lds_dwordx4 v[16:17], off
	s_waitcnt vmcnt(8)
	s_waitcnt lgkmcnt(0)
	s_barrier
	s_setprio 1
	v_mfma_f32_16x16x128_f8f6f4 v[56:59], v[0:7], v[24:31], v[56:59]
	v_mfma_f32_16x16x128_f8f6f4 v[60:63], v[8:15], v[24:31], v[60:63]
	v_mfma_f32_16x16x128_f8f6f4 v[48:51], v[0:7], v[144:151], v[48:51]
	v_mfma_f32_16x16x128_f8f6f4 v[52:55], v[8:15], v[144:151], v[52:55]
	v_mfma_f32_16x16x128_f8f6f4 v[32:35], v[0:7], v[152:159], v[32:35]
	v_mfma_f32_16x16x128_f8f6f4 v[36:39], v[8:15], v[152:159], v[224:227]
	v_mfma_f32_16x16x128_f8f6f4 v[16:19], v[0:7], v[192:199], v[228:231]
	v_mfma_f32_16x16x128_f8f6f4 v[20:23], v[8:15], v[192:199], v[232:235]
	v_mfma_f32_16x16x128_f8f6f4 v[40:43], v[128:135], v[24:31], v[236:239]
	v_mfma_f32_16x16x128_f8f6f4 v[44:47], v[136:143], v[24:31], v[44:47]
	v_mfma_f32_16x16x128_f8f6f4 v[24:27], v[128:135], v[144:151], v[240:243]
	v_mfma_f32_16x16x128_f8f6f4 v[28:31], v[136:143], v[144:151], v[200:203]
	v_mfma_f32_16x16x128_f8f6f4 v[8:11], v[128:135], v[152:159], v[204:207]
	v_mfma_f32_16x16x128_f8f6f4 v[12:15], v[136:143], v[152:159], v[208:211]
	v_mfma_f32_16x16x128_f8f6f4 v[0:3], v[128:135], v[192:199], v[212:215]
	v_mfma_f32_16x16x128_f8f6f4 v[4:7], v[136:143], v[192:199], v[216:219]
	s_setprio 0
	s_barrier
	s_add_u32 s24, s24, 0x100
	s_addc_u32 s25, s25, 0
	s_add_u32 s82, s82, 0x100
	s_addc_u32 s83, s83, 0
	s_cmp_ge_u32 s42, s80
	s_mov_b32 s26, s42
	s_cbranch_scc0 .LBB0_2536
	s_and_b64 vcc, exec, s[16:17]
	s_cbranch_vccz .LBB0_2539
	s_barrier
